# attention: softmax VALU interleaved into the compute wave's own MFMA gaps, load-only partner phase; GEMM: address VALU hoisted before barrier, half of LDS-DMA issues moved into MFMA phase
# speedup vs baseline: 1.0203x; 1.0203x over previous
; #define STAGE_ALL(bufi, kt) do { STAGEA(SA(bufi, 0), brow, kt); STAGEA(SA(bufi, 1), brow + HALF, kt); STAGEB(SB(bufi), bcol, kt); } while (0)
; #define WAIT_V(n) asm volatile("s_waitcnt vmcnt(" #n ")" ::: "memory")
; #define BAR __builtin_amdgcn_s_barrier()
;     ...
;   const int wid = tid >> 6, lane = tid & 63, wr = wid >> 1, wc = wid & 1, fr = lane & 15, fq = lane >> 4;
;   acc_t acc;
; #pragma unroll
;   for (int m = 0; m < 4; ++m)
; #pragma unroll
;     for (int n = 0; n < 4; ++n) acc[m][n] = f32x4{0.f, 0.f, 0.f, 0.f};
;   const int nt = K / BK;
;   unsigned oA0, oA1, oB0, oB1;
;   { int _r, _c; stage_rc(tid * 16, _r, _c); oA0 = _r * lda + _c; oB0 = _r * ldb + _c;
;     stage_rc(tid * 16 + 8192, _r, _c); oA1 = _r * lda + _c; oB1 = _r * ldb + _c; }
;     ...
;     for (int t = 0; t < nt; ++t) {
;       const char* pa = (const char*)SA(b, wr >> 1);
;       const char* pb = (const char*)SB(b);
;       bf16x8 At[4][2], Bf[4][2];
; #pragma unroll
;       for (int m = 0; m < 4; ++m)
; #pragma unroll
;         for (int k = 0; k < 2; ++k) At[m][k] = *reinterpret_cast<const bf16x8*>(pa + lds_byte((wr & 1) * 64 + m * 16 + fr, k * 32 + fq * 8));
; #pragma unroll
;       for (int n = 0; n < 4; ++n)
; #pragma unroll
;         for (int k = 0; k < 2; ++k) Bf[n][k] = *reinterpret_cast<const bf16x8*>(pb + lds_byte(wc * 64 + n * 16 + fr, k * 32 + fq * 8));
;       if (t + 2 < nt) { const int b2 = (b == 0) ? 2 : b - 1; STAGE_ALL(b2, t + 2); WAIT_V(6); } else { WAIT_V(0); }
;       asm volatile("s_waitcnt lgkmcnt(0)" ::: "memory");
;       __builtin_amdgcn_sched_barrier(0);
;       BAR;
;       __builtin_amdgcn_sched_barrier(0);
;       __builtin_amdgcn_s_setprio(1);
; #pragma unroll
;       for (int k = 0; k < 2; ++k)
; #pragma unroll
;         for (int m = 0; m < 4; ++m)
; #pragma unroll
;           for (int n = 0; n < 4; ++n) acc[m][n] = __builtin_amdgcn_mfma_f32_16x16x32_bf16(Bf[n][k], At[m][k], acc[m][n], 0, 0, 0);
.LBB0_40:
	s_or_b64 exec, exec, s[10:11]
	v_and_b32_e32 v8, 15, v133
	v_and_b32_e32 v9, 48, v133
	v_lshl_or_b32 v8, v8, 6, v9
	v_lshlrev_b32_e32 v9, 2, v133
	v_and_b32_e32 v9, 32, v9
	v_xad_u32 v8, v8, v9, 16
	v_lshlrev_b32_e32 v9, 6, v133
	v_lshlrev_b32_e32 v10, 7, v133
	v_and_b32_e32 v9, 0x2000, v9
	v_and_b32_e32 v10, 0x2000, v10
	v_add_u32_e32 v129, v8, v9
	v_add_u32_e32 v131, v8, v10
	v_lshrrev_b32_e32 v8, 1, v4
	v_mul_lo_u32 v4, v6, s66
	s_mov_b32 s61, 0xb000
	v_mad_u64_u32 v[8:9], s[10:11], v8, s61, v[4:5]
	v_or_b32_e32 v4, v8, v5
	s_add_u32 s10, s47, s41
	v_lshrrev_b32_e32 v6, 1, v0
	v_mul_lo_u32 v0, v2, s66
	v_add_u32_sdwa v196, v4, sext(v7) dst_sel:DWORD dst_unused:UNUSED_PAD src0_sel:DWORD src1_sel:WORD_0
	s_addc_u32 s11, s48, s40
	v_mad_u64_u32 v[6:7], s[40:41], v6, s61, v[0:1]
	v_or_b32_e32 v0, v6, v1
	v_lshlrev_b64 v[4:5], 1, v[196:197]
	v_add_u32_sdwa v196, v0, sext(v3) dst_sel:DWORD dst_unused:UNUSED_PAD src0_sel:DWORD src1_sel:WORD_0
	v_lshlrev_b64 v[0:1], 1, v[196:197]
	v_lshl_add_u64 v[134:135], s[10:11], 0, v[4:5]
	v_lshl_add_u64 v[136:137], s[10:11], 0, v[0:1]
	s_add_u32 s10, s54, s37
	s_addc_u32 s11, s55, s36
	v_mov_b32_e32 v60, 0
	v_ashrrev_i32_e32 v132, 8, v133
	v_lshl_add_u64 v[138:139], s[10:11], 0, v[4:5]
	v_lshl_add_u64 v[140:141], s[10:11], 0, v[0:1]
	s_mov_b32 s61, 0
	s_mov_b64 s[10:11], 0
	s_mov_b32 s62, 0
	v_mov_b32_e32 v61, v60
	v_mov_b32_e32 v62, v60
	v_mov_b32_e32 v63, v60
	v_mov_b32_e32 v56, v60
	v_mov_b32_e32 v57, v60
	v_mov_b32_e32 v58, v60
	v_mov_b32_e32 v59, v60
	v_mov_b32_e32 v52, v60
	v_mov_b32_e32 v53, v60
	v_mov_b32_e32 v54, v60
	v_mov_b32_e32 v55, v60
	v_mov_b32_e32 v48, v60
	v_mov_b32_e32 v49, v60
	v_mov_b32_e32 v50, v60
	v_mov_b32_e32 v51, v60
	v_mov_b32_e32 v44, v60
	v_mov_b32_e32 v45, v60
	v_mov_b32_e32 v46, v60
	v_mov_b32_e32 v47, v60
	v_mov_b32_e32 v40, v60
	v_mov_b32_e32 v41, v60
	v_mov_b32_e32 v42, v60
	v_mov_b32_e32 v43, v60
	v_mov_b32_e32 v36, v60
	v_mov_b32_e32 v37, v60
	v_mov_b32_e32 v38, v60
	v_mov_b32_e32 v39, v60
	v_mov_b32_e32 v32, v60
	v_mov_b32_e32 v33, v60
	v_mov_b32_e32 v34, v60
	v_mov_b32_e32 v35, v60
	v_mov_b32_e32 v28, v60
	v_mov_b32_e32 v29, v60
	v_mov_b32_e32 v30, v60
	v_mov_b32_e32 v31, v60
	v_mov_b32_e32 v24, v60
	v_mov_b32_e32 v25, v60
	v_mov_b32_e32 v26, v60
	v_mov_b32_e32 v27, v60
	v_mov_b32_e32 v20, v60
	v_mov_b32_e32 v21, v60
	v_mov_b32_e32 v22, v60
	v_mov_b32_e32 v23, v60
	v_mov_b32_e32 v16, v60
	v_mov_b32_e32 v17, v60
	v_mov_b32_e32 v18, v60
	v_mov_b32_e32 v19, v60
	v_mov_b32_e32 v12, v60
	v_mov_b32_e32 v13, v60
	v_mov_b32_e32 v14, v60
	v_mov_b32_e32 v15, v60
	v_mov_b32_e32 v8, v60
	v_mov_b32_e32 v9, v60
	v_mov_b32_e32 v10, v60
	v_mov_b32_e32 v11, v60
	v_mov_b32_e32 v4, v60
	v_mov_b32_e32 v5, v60
	v_mov_b32_e32 v6, v60
	v_mov_b32_e32 v7, v60
	v_mov_b32_e32 v0, v60
	v_mov_b32_e32 v1, v60
	v_mov_b32_e32 v2, v60
	v_mov_b32_e32 v3, v60
	v_readfirstlane_b32 s99, v151
	v_lshl_add_u32 v174, v132, 14, v129
	v_mov_b32_e32 v161, v131
	v_lshl_add_u64 v[162:163], v[140:141], 0, s[16:17]
	v_lshl_add_u64 v[164:165], v[138:139], 0, s[16:17]
	v_lshl_add_u64 v[166:167], v[140:141], 0, s[18:19]
	v_lshl_add_u64 v[168:169], v[138:139], 0, s[18:19]
	v_mov_b64_e32 v[170:171], v[136:137]
	v_mov_b64_e32 v[172:173], v[134:135]
	v_mov_b32_e32 v160, v174
	s_add_u32 s98, s99, 0x18000
	s_branch .LBB0_42
.LBB0_41:
	s_waitcnt lgkmcnt(0)
	s_barrier
	s_setprio 1
	s_waitcnt lgkmcnt(0)
	v_mfma_f32_16x16x32_bf16 v[60:63], v[112:115], v[108:111], v[60:63]
	v_mfma_f32_16x16x32_bf16 v[56:59], v[116:119], v[108:111], v[56:59]
	v_mfma_f32_16x16x32_bf16 v[52:55], v[120:123], v[108:111], v[52:55]
	v_mfma_f32_16x16x32_bf16 v[48:51], v[124:127], v[108:111], v[48:51]
	v_mfma_f32_16x16x32_bf16 v[44:47], v[112:115], v[104:107], v[44:47]
	v_mfma_f32_16x16x32_bf16 v[40:43], v[116:119], v[104:107], v[40:43]
	v_mfma_f32_16x16x32_bf16 v[36:39], v[120:123], v[104:107], v[36:39]
	v_mfma_f32_16x16x32_bf16 v[32:35], v[124:127], v[104:107], v[32:35]
	s_cmp_gt_u32 s62, 41
	s_cbranch_scc1 .Lgc1_skd3
	s_add_u32 m0, s98, 0x6000
	s_nop 0
	global_load_lds_dwordx4 v[168:169], off
; #define STAGE_ALL(bufi, kt) do { STAGEA(SA(bufi, 0), brow, kt); STAGEA(SA(bufi, 1), brow + HALF, kt); STAGEB(SB(bufi), bcol, kt); } while (0)
; #define WAIT_V(n) asm volatile("s_waitcnt vmcnt(" #n ")" ::: "memory")
; #define BAR __builtin_amdgcn_s_barrier()
;     ...
;     for (int t = 0; t < nt; ++t) {
;       const char* pa = (const char*)SA(b, wr >> 1);
;       const char* pb = (const char*)SB(b);
;       bf16x8 At[4][2], Bf[4][2];
; #pragma unroll
;       for (int m = 0; m < 4; ++m)
; #pragma unroll
;         for (int k = 0; k < 2; ++k) At[m][k] = *reinterpret_cast<const bf16x8*>(pa + lds_byte((wr & 1) * 64 + m * 16 + fr, k * 32 + fq * 8));
; #pragma unroll
;       for (int n = 0; n < 4; ++n)
; #pragma unroll
;         for (int k = 0; k < 2; ++k) Bf[n][k] = *reinterpret_cast<const bf16x8*>(pb + lds_byte(wc * 64 + n * 16 + fr, k * 32 + fq * 8));
;       if (t + 2 < nt) { const int b2 = (b == 0) ? 2 : b - 1; STAGE_ALL(b2, t + 2); WAIT_V(6); } else { WAIT_V(0); }
;       asm volatile("s_waitcnt lgkmcnt(0)" ::: "memory");
;       __builtin_amdgcn_sched_barrier(0);
;       BAR;
;       __builtin_amdgcn_sched_barrier(0);
;       __builtin_amdgcn_s_setprio(1);
; #pragma unroll
;       for (int k = 0; k < 2; ++k)
; #pragma unroll
;         for (int m = 0; m < 4; ++m)
; #pragma unroll
;           for (int n = 0; n < 4; ++n) acc[m][n] = __builtin_amdgcn_mfma_f32_16x16x32_bf16(Bf[n][k], At[m][k], acc[m][n], 0, 0, 0);
;       __builtin_amdgcn_s_setprio(0);
;       __builtin_amdgcn_sched_barrier(0);
;       BAR;
;       __builtin_amdgcn_sched_barrier(0);
;       b = (b == 2) ? 0 : b + 1;
;     }
.Lgc1_skd3:
	v_mfma_f32_16x16x32_bf16 v[28:31], v[112:115], v[100:103], v[28:31]
	v_mfma_f32_16x16x32_bf16 v[24:27], v[116:119], v[100:103], v[24:27]
	v_mfma_f32_16x16x32_bf16 v[20:23], v[120:123], v[100:103], v[20:23]
	v_mfma_f32_16x16x32_bf16 v[16:19], v[124:127], v[100:103], v[16:19]
	v_mfma_f32_16x16x32_bf16 v[12:15], v[112:115], v[96:99], v[12:15]
	v_mfma_f32_16x16x32_bf16 v[8:11], v[116:119], v[96:99], v[8:11]
	v_mfma_f32_16x16x32_bf16 v[4:7], v[120:123], v[96:99], v[4:7]
	v_mfma_f32_16x16x32_bf16 v[0:3], v[124:127], v[96:99], v[0:3]
	s_cmp_gt_u32 s62, 41
	s_cbranch_scc1 .Lgc1_skd4
	s_add_u32 m0, s98, 0x8000
	s_nop 0
	global_load_lds_dwordx4 v[170:171], off
.Lgc1_skd4:
	v_mfma_f32_16x16x32_bf16 v[60:63], v[80:83], v[76:79], v[60:63]
	v_mfma_f32_16x16x32_bf16 v[56:59], v[84:87], v[76:79], v[56:59]
	v_mfma_f32_16x16x32_bf16 v[52:55], v[88:91], v[76:79], v[52:55]
	v_mfma_f32_16x16x32_bf16 v[48:51], v[92:95], v[76:79], v[48:51]
	v_mfma_f32_16x16x32_bf16 v[44:47], v[80:83], v[72:75], v[44:47]
	v_mfma_f32_16x16x32_bf16 v[40:43], v[84:87], v[72:75], v[40:43]
	v_mfma_f32_16x16x32_bf16 v[36:39], v[88:91], v[72:75], v[36:39]
	v_mfma_f32_16x16x32_bf16 v[32:35], v[92:95], v[72:75], v[32:35]
	s_cmp_gt_u32 s62, 41
	s_cbranch_scc1 .Lgc1_skd5
	s_add_u32 m0, s98, 0xa000
	s_nop 0
	global_load_lds_dwordx4 v[172:173], off
.Lgc1_skd5:
	v_mfma_f32_16x16x32_bf16 v[28:31], v[80:83], v[68:71], v[28:31]
	v_mfma_f32_16x16x32_bf16 v[24:27], v[84:87], v[68:71], v[24:27]
	v_mfma_f32_16x16x32_bf16 v[20:23], v[88:91], v[68:71], v[20:23]
	v_mfma_f32_16x16x32_bf16 v[16:19], v[92:95], v[68:71], v[16:19]
	v_mfma_f32_16x16x32_bf16 v[12:15], v[80:83], v[64:67], v[12:15]
	v_mfma_f32_16x16x32_bf16 v[8:11], v[84:87], v[64:67], v[8:11]
	v_mfma_f32_16x16x32_bf16 v[4:7], v[88:91], v[64:67], v[4:7]
	v_mfma_f32_16x16x32_bf16 v[0:3], v[92:95], v[64:67], v[0:3]
	s_setprio 0
	s_add_i32 s36, s61, 1
	s_cmp_lg_u32 s61, 2
	s_cselect_b32 s61, s36, 0
	s_add_i32 s62, s62, 1
	s_add_u32 s10, s10, 0x80
	s_addc_u32 s11, s11, 0
	s_mul_i32 s36, s61, 0xc000
	v_add_u32_e32 v160, s36, v174
	v_add_u32_e32 v161, s36, v131
	s_mul_i32 s36, s61, 0x6000
	s_addk_i32 s36, 0xa000
	s_cmp_lg_u32 s61, 0
	s_cselect_b32 s36, s36, 0xc000
	s_lshl_b32 s36, s36, 1
	s_add_u32 s98, s36, s99
	v_lshl_add_u64 v[162:163], v[162:163], 0, s[14:15]
	v_lshl_add_u64 v[164:165], v[164:165], 0, s[14:15]
	v_lshl_add_u64 v[166:167], v[166:167], 0, s[14:15]
	v_lshl_add_u64 v[168:169], v[168:169], 0, s[14:15]
	v_lshl_add_u64 v[170:171], v[170:171], 0, s[14:15]
	v_lshl_add_u64 v[172:173], v[172:173], 0, s[14:15]
	s_barrier
	s_cmpk_eq_i32 s10, 0x1600
	s_cbranch_scc1 .LBB0_46
.LBB0_42:
	ds_read_b128 v[108:111], v160
	ds_read_b128 v[76:79], v160 offset:1024
	ds_read_b128 v[104:107], v160 offset:2048
	ds_read_b128 v[72:75], v160 offset:3072
	ds_read_b128 v[100:103], v160 offset:4096
	ds_read_b128 v[68:71], v160 offset:5120
	ds_read_b128 v[96:99], v160 offset:6144
	ds_read_b128 v[64:67], v160 offset:7168
	ds_read_b128 v[112:115], v161 offset:32768
	ds_read_b128 v[80:83], v161 offset:33792
	ds_read_b128 v[116:119], v161 offset:34816
	ds_read_b128 v[84:87], v161 offset:35840
	ds_read_b128 v[120:123], v161 offset:36864
	ds_read_b128 v[88:91], v161 offset:37888
	ds_read_b128 v[124:127], v161 offset:38912
	ds_read_b128 v[92:95], v161 offset:39936
	s_cmp_gt_u32 s62, 41
	s_cbranch_scc1 .Lgc1_nostage
	s_mov_b32 m0, s98
	s_nop 0
	global_load_lds_dwordx4 v[162:163], off
	s_add_u32 m0, s98, 0x2000
	s_nop 0
	global_load_lds_dwordx4 v[164:165], off
	s_add_u32 m0, s98, 0x4000
	s_nop 0
	global_load_lds_dwordx4 v[166:167], off
	s_waitcnt vmcnt(3)
	s_branch .LBB0_41
.Lgc1_nostage:
	s_waitcnt vmcnt(0)
	s_branch .LBB0_41

; #define STAGE_ALL(bufi, kt) do { STAGEA(SA(bufi, 0), brow, kt); STAGEA(SA(bufi, 1), brow + HALF, kt); STAGEB(SB(bufi), bcol, kt); } while (0)
; #define WAIT_V(n) asm volatile("s_waitcnt vmcnt(" #n ")" ::: "memory")
; #define BAR __builtin_amdgcn_s_barrier()
;     ...
;   const int wid = tid >> 6, lane = tid & 63, wr = wid >> 1, wc = wid & 1, fr = lane & 15, fq = lane >> 4;
;   acc_t acc;
; #pragma unroll
;   for (int m = 0; m < 4; ++m)
; #pragma unroll
;     for (int n = 0; n < 4; ++n) acc[m][n] = f32x4{0.f, 0.f, 0.f, 0.f};
;   const int nt = K / BK;
;   unsigned oA0, oA1, oB0, oB1;
;   { int _r, _c; stage_rc(tid * 16, _r, _c); oA0 = _r * lda + _c; oB0 = _r * ldb + _c;
;     stage_rc(tid * 16 + 8192, _r, _c); oA1 = _r * lda + _c; oB1 = _r * ldb + _c; }
;     ...
;     for (int t = 0; t < nt; ++t) {
;       const char* pa = (const char*)SA(b, wr >> 1);
;       const char* pb = (const char*)SB(b);
;       bf16x8 At[4][2], Bf[4][2];
; #pragma unroll
;       for (int m = 0; m < 4; ++m)
; #pragma unroll
;         for (int k = 0; k < 2; ++k) At[m][k] = *reinterpret_cast<const bf16x8*>(pa + lds_byte((wr & 1) * 64 + m * 16 + fr, k * 32 + fq * 8));
; #pragma unroll
;       for (int n = 0; n < 4; ++n)
; #pragma unroll
;         for (int k = 0; k < 2; ++k) Bf[n][k] = *reinterpret_cast<const bf16x8*>(pb + lds_byte(wc * 64 + n * 16 + fr, k * 32 + fq * 8));
;       if (t + 2 < nt) { const int b2 = (b == 0) ? 2 : b - 1; STAGE_ALL(b2, t + 2); WAIT_V(6); } else { WAIT_V(0); }
;       asm volatile("s_waitcnt lgkmcnt(0)" ::: "memory");
;       __builtin_amdgcn_sched_barrier(0);
;       BAR;
;       __builtin_amdgcn_sched_barrier(0);
;       __builtin_amdgcn_s_setprio(1);
; #pragma unroll
;       for (int k = 0; k < 2; ++k)
; #pragma unroll
;         for (int m = 0; m < 4; ++m)
; #pragma unroll
;           for (int n = 0; n < 4; ++n) acc[m][n] = __builtin_amdgcn_mfma_f32_16x16x32_bf16(Bf[n][k], At[m][k], acc[m][n], 0, 0, 0);
.LBB0_72:
	s_or_b64 exec, exec, s[44:45]
	v_lshlrev_b32_e32 v4, 13, v4
	v_and_b32_e32 v4, 0xffffc000, v4
	v_lshlrev_b32_e32 v0, 13, v0
	v_lshl_add_u32 v4, v5, 10, v4
	v_and_b32_e32 v0, 0xffffc000, v0
	s_ashr_i32 s43, s42, 31
	s_ashr_i32 s11, s10, 31
	v_or_b32_e32 v4, v4, v6
	v_lshl_add_u32 v0, v1, 10, v0
	v_and_b32_e32 v8, 15, v133
	v_and_b32_e32 v9, 48, v133
	s_lshl_b64 s[36:37], s[42:43], 11
	s_lshl_b64 s[10:11], s[10:11], 11
	v_add_u32_sdwa v196, v4, sext(v7) dst_sel:DWORD dst_unused:UNUSED_PAD src0_sel:DWORD src1_sel:WORD_0
	v_or_b32_e32 v0, v0, v2
	v_lshl_or_b32 v8, v8, 6, v9
	v_lshlrev_b32_e32 v9, 2, v133
	v_lshlrev_b64 v[4:5], 1, v[196:197]
	s_add_u32 s10, s51, s10
	v_add_u32_sdwa v196, v0, sext(v3) dst_sel:DWORD dst_unused:UNUSED_PAD src0_sel:DWORD src1_sel:WORD_0
	v_and_b32_e32 v9, 32, v9
	s_addc_u32 s11, s58, s11
	v_lshlrev_b64 v[0:1], 1, v[196:197]
	v_xad_u32 v8, v8, v9, 16
	v_lshlrev_b32_e32 v9, 6, v133
	v_lshlrev_b32_e32 v10, 7, v133
	v_lshl_add_u64 v[134:135], s[10:11], 0, v[4:5]
	v_lshl_add_u64 v[136:137], s[10:11], 0, v[0:1]
	s_add_u32 s10, s54, s36
	v_and_b32_e32 v9, 0x2000, v9
	v_and_b32_e32 v10, 0x2000, v10
	s_addc_u32 s11, s55, s37
	v_mov_b32_e32 v56, 0
	v_ashrrev_i32_e32 v132, 8, v133
	v_add_u32_e32 v129, v8, v9
	v_add_u32_e32 v131, v8, v10
	v_lshl_add_u64 v[138:139], s[10:11], 0, v[4:5]
	v_lshl_add_u64 v[140:141], s[10:11], 0, v[0:1]
	s_mov_b32 s43, 0
	s_mov_b64 s[10:11], 0
	s_mov_b32 s64, 0
	v_mov_b32_e32 v57, v56
	v_mov_b32_e32 v58, v56
	v_mov_b32_e32 v59, v56
	v_mov_b32_e32 v48, v56
	v_mov_b32_e32 v49, v56
	v_mov_b32_e32 v50, v56
	v_mov_b32_e32 v51, v56
	v_mov_b32_e32 v60, v56
	v_mov_b32_e32 v61, v56
	v_mov_b32_e32 v62, v56
	v_mov_b32_e32 v63, v56
	v_mov_b32_e32 v52, v56
	v_mov_b32_e32 v53, v56
	v_mov_b32_e32 v54, v56
	v_mov_b32_e32 v55, v56
	v_mov_b32_e32 v40, v56
	v_mov_b32_e32 v41, v56
	v_mov_b32_e32 v42, v56
	v_mov_b32_e32 v43, v56
	v_mov_b32_e32 v32, v56
	v_mov_b32_e32 v33, v56
	v_mov_b32_e32 v34, v56
	v_mov_b32_e32 v35, v56
	v_mov_b32_e32 v44, v56
	v_mov_b32_e32 v45, v56
	v_mov_b32_e32 v46, v56
	v_mov_b32_e32 v47, v56
	v_mov_b32_e32 v36, v56
	v_mov_b32_e32 v37, v56
	v_mov_b32_e32 v38, v56
	v_mov_b32_e32 v39, v56
	v_mov_b32_e32 v24, v56
	v_mov_b32_e32 v25, v56
	v_mov_b32_e32 v26, v56
	v_mov_b32_e32 v27, v56
	v_mov_b32_e32 v16, v56
	v_mov_b32_e32 v17, v56
	v_mov_b32_e32 v18, v56
	v_mov_b32_e32 v19, v56
	v_mov_b32_e32 v28, v56
	v_mov_b32_e32 v29, v56
	v_mov_b32_e32 v30, v56
	v_mov_b32_e32 v31, v56
	v_mov_b32_e32 v20, v56
	v_mov_b32_e32 v21, v56
	v_mov_b32_e32 v22, v56
	v_mov_b32_e32 v23, v56
	v_mov_b32_e32 v8, v56
	v_mov_b32_e32 v9, v56
	v_mov_b32_e32 v10, v56
	v_mov_b32_e32 v11, v56
	v_mov_b32_e32 v0, v56
	v_mov_b32_e32 v1, v56
	v_mov_b32_e32 v2, v56
	v_mov_b32_e32 v3, v56
	v_mov_b32_e32 v12, v56
	v_mov_b32_e32 v13, v56
	v_mov_b32_e32 v14, v56
	v_mov_b32_e32 v15, v56
	v_mov_b32_e32 v4, v56
	v_mov_b32_e32 v5, v56
	v_mov_b32_e32 v6, v56
	v_mov_b32_e32 v7, v56
	v_readfirstlane_b32 s99, v151
	v_lshl_add_u32 v174, v132, 14, v129
	v_mov_b32_e32 v161, v131
	v_lshl_add_u64 v[162:163], v[140:141], 0, s[20:21]
	v_lshl_add_u64 v[164:165], v[138:139], 0, s[20:21]
	v_lshl_add_u64 v[166:167], v[140:141], 0, s[22:23]
	v_lshl_add_u64 v[168:169], v[138:139], 0, s[22:23]
	v_mov_b64_e32 v[170:171], v[136:137]
	v_mov_b64_e32 v[172:173], v[134:135]
	v_mov_b32_e32 v160, v174
	s_add_u32 s98, s99, 0x18000
	s_branch .LBB0_74
.LBB0_73:
	s_waitcnt lgkmcnt(0)
	s_barrier
	s_setprio 1
	s_waitcnt lgkmcnt(0)
	v_mfma_f32_16x16x32_bf16 v[56:59], v[112:115], v[108:111], v[56:59]
	v_mfma_f32_16x16x32_bf16 v[48:51], v[116:119], v[108:111], v[48:51]
	v_mfma_f32_16x16x32_bf16 v[60:63], v[120:123], v[108:111], v[60:63]
	v_mfma_f32_16x16x32_bf16 v[52:55], v[124:127], v[108:111], v[52:55]
	v_mfma_f32_16x16x32_bf16 v[40:43], v[112:115], v[104:107], v[40:43]
	v_mfma_f32_16x16x32_bf16 v[32:35], v[116:119], v[104:107], v[32:35]
	v_mfma_f32_16x16x32_bf16 v[44:47], v[120:123], v[104:107], v[44:47]
	v_mfma_f32_16x16x32_bf16 v[36:39], v[124:127], v[104:107], v[36:39]
	s_cmp_gt_u32 s64, 13
	s_cbranch_scc1 .Lgc2_skd3
	s_add_u32 m0, s98, 0x6000
	s_nop 0
	global_load_lds_dwordx4 v[168:169], off
; #define STAGE_ALL(bufi, kt) do { STAGEA(SA(bufi, 0), brow, kt); STAGEA(SA(bufi, 1), brow + HALF, kt); STAGEB(SB(bufi), bcol, kt); } while (0)
; #define WAIT_V(n) asm volatile("s_waitcnt vmcnt(" #n ")" ::: "memory")
; #define BAR __builtin_amdgcn_s_barrier()
;     ...
;     for (int t = 0; t < nt; ++t) {
;       const char* pa = (const char*)SA(b, wr >> 1);
;       const char* pb = (const char*)SB(b);
;       bf16x8 At[4][2], Bf[4][2];
; #pragma unroll
;       for (int m = 0; m < 4; ++m)
; #pragma unroll
;         for (int k = 0; k < 2; ++k) At[m][k] = *reinterpret_cast<const bf16x8*>(pa + lds_byte((wr & 1) * 64 + m * 16 + fr, k * 32 + fq * 8));
; #pragma unroll
;       for (int n = 0; n < 4; ++n)
; #pragma unroll
;         for (int k = 0; k < 2; ++k) Bf[n][k] = *reinterpret_cast<const bf16x8*>(pb + lds_byte(wc * 64 + n * 16 + fr, k * 32 + fq * 8));
;       if (t + 2 < nt) { const int b2 = (b == 0) ? 2 : b - 1; STAGE_ALL(b2, t + 2); WAIT_V(6); } else { WAIT_V(0); }
;       asm volatile("s_waitcnt lgkmcnt(0)" ::: "memory");
;       __builtin_amdgcn_sched_barrier(0);
;       BAR;
;       __builtin_amdgcn_sched_barrier(0);
;       __builtin_amdgcn_s_setprio(1);
; #pragma unroll
;       for (int k = 0; k < 2; ++k)
; #pragma unroll
;         for (int m = 0; m < 4; ++m)
; #pragma unroll
;           for (int n = 0; n < 4; ++n) acc[m][n] = __builtin_amdgcn_mfma_f32_16x16x32_bf16(Bf[n][k], At[m][k], acc[m][n], 0, 0, 0);
;       __builtin_amdgcn_s_setprio(0);
;       __builtin_amdgcn_sched_barrier(0);
;       BAR;
;       __builtin_amdgcn_sched_barrier(0);
;       b = (b == 2) ? 0 : b + 1;
;     }
.Lgc2_skd3:
	v_mfma_f32_16x16x32_bf16 v[24:27], v[112:115], v[100:103], v[24:27]
	v_mfma_f32_16x16x32_bf16 v[16:19], v[116:119], v[100:103], v[16:19]
	v_mfma_f32_16x16x32_bf16 v[28:31], v[120:123], v[100:103], v[28:31]
	v_mfma_f32_16x16x32_bf16 v[20:23], v[124:127], v[100:103], v[20:23]
	v_mfma_f32_16x16x32_bf16 v[8:11], v[112:115], v[96:99], v[8:11]
	v_mfma_f32_16x16x32_bf16 v[0:3], v[116:119], v[96:99], v[0:3]
	v_mfma_f32_16x16x32_bf16 v[12:15], v[120:123], v[96:99], v[12:15]
	v_mfma_f32_16x16x32_bf16 v[4:7], v[124:127], v[96:99], v[4:7]
	s_cmp_gt_u32 s64, 13
	s_cbranch_scc1 .Lgc2_skd4
	s_add_u32 m0, s98, 0x8000
	s_nop 0
	global_load_lds_dwordx4 v[170:171], off
.Lgc2_skd4:
	v_mfma_f32_16x16x32_bf16 v[56:59], v[80:83], v[76:79], v[56:59]
	v_mfma_f32_16x16x32_bf16 v[48:51], v[84:87], v[76:79], v[48:51]
	v_mfma_f32_16x16x32_bf16 v[60:63], v[88:91], v[76:79], v[60:63]
	v_mfma_f32_16x16x32_bf16 v[52:55], v[92:95], v[76:79], v[52:55]
	v_mfma_f32_16x16x32_bf16 v[40:43], v[80:83], v[72:75], v[40:43]
	v_mfma_f32_16x16x32_bf16 v[32:35], v[84:87], v[72:75], v[32:35]
	v_mfma_f32_16x16x32_bf16 v[44:47], v[88:91], v[72:75], v[44:47]
	v_mfma_f32_16x16x32_bf16 v[36:39], v[92:95], v[72:75], v[36:39]
	s_cmp_gt_u32 s64, 13
	s_cbranch_scc1 .Lgc2_skd5
	s_add_u32 m0, s98, 0xa000
	s_nop 0
	global_load_lds_dwordx4 v[172:173], off
.Lgc2_skd5:
	v_mfma_f32_16x16x32_bf16 v[24:27], v[80:83], v[68:71], v[24:27]
	v_mfma_f32_16x16x32_bf16 v[16:19], v[84:87], v[68:71], v[16:19]
	v_mfma_f32_16x16x32_bf16 v[28:31], v[88:91], v[68:71], v[28:31]
	v_mfma_f32_16x16x32_bf16 v[20:23], v[92:95], v[68:71], v[20:23]
	v_mfma_f32_16x16x32_bf16 v[8:11], v[80:83], v[64:67], v[8:11]
	v_mfma_f32_16x16x32_bf16 v[0:3], v[84:87], v[64:67], v[0:3]
	v_mfma_f32_16x16x32_bf16 v[12:15], v[88:91], v[64:67], v[12:15]
	v_mfma_f32_16x16x32_bf16 v[4:7], v[92:95], v[64:67], v[4:7]
	s_setprio 0
	s_add_i32 s36, s43, 1
	s_cmp_lg_u32 s43, 2
	s_cselect_b32 s43, s36, 0
	s_add_i32 s64, s64, 1
	s_add_u32 s10, s10, 0x80
	s_addc_u32 s11, s11, 0
	s_mul_i32 s36, s43, 0xc000
	v_add_u32_e32 v160, s36, v174
	v_add_u32_e32 v161, s36, v131
	s_mul_i32 s36, s43, 0x6000
	s_addk_i32 s36, 0xa000
	s_cmp_lg_u32 s43, 0
	s_cselect_b32 s36, s36, 0xc000
	s_lshl_b32 s36, s36, 1
	s_add_u32 s98, s36, s99
	v_lshl_add_u64 v[162:163], v[162:163], 0, s[14:15]
	v_lshl_add_u64 v[164:165], v[164:165], 0, s[14:15]
	v_lshl_add_u64 v[166:167], v[166:167], 0, s[14:15]
	v_lshl_add_u64 v[168:169], v[168:169], 0, s[14:15]
	v_lshl_add_u64 v[170:171], v[170:171], 0, s[14:15]
	v_lshl_add_u64 v[172:173], v[172:173], 0, s[14:15]
	s_barrier
	s_cmpk_eq_i32 s10, 0x800
	s_cbranch_scc1 .LBB0_78
.LBB0_74:
	ds_read_b128 v[108:111], v160
	ds_read_b128 v[76:79], v160 offset:1024
	ds_read_b128 v[104:107], v160 offset:2048
	ds_read_b128 v[72:75], v160 offset:3072
	ds_read_b128 v[100:103], v160 offset:4096
	ds_read_b128 v[68:71], v160 offset:5120
	ds_read_b128 v[96:99], v160 offset:6144
	ds_read_b128 v[64:67], v160 offset:7168
	ds_read_b128 v[112:115], v161 offset:32768
	ds_read_b128 v[80:83], v161 offset:33792
	ds_read_b128 v[116:119], v161 offset:34816
	ds_read_b128 v[84:87], v161 offset:35840
	ds_read_b128 v[120:123], v161 offset:36864
	ds_read_b128 v[88:91], v161 offset:37888
	ds_read_b128 v[124:127], v161 offset:38912
	ds_read_b128 v[92:95], v161 offset:39936
	s_cmp_gt_u32 s64, 13
	s_cbranch_scc1 .Lgc2_nostage
	s_mov_b32 m0, s98
	s_nop 0
	global_load_lds_dwordx4 v[162:163], off
	s_add_u32 m0, s98, 0x2000
	s_nop 0
	global_load_lds_dwordx4 v[164:165], off
	s_add_u32 m0, s98, 0x4000
	s_nop 0
	global_load_lds_dwordx4 v[166:167], off
	s_waitcnt vmcnt(3)
	s_branch .LBB0_73

; #define STAGE_ALL(bufi, kt) do { STAGEA(SA(bufi, 0), brow, kt); STAGEA(SA(bufi, 1), brow + HALF, kt); STAGEB(SB(bufi), bcol, kt); } while (0)
; #define WAIT_V(n) asm volatile("s_waitcnt vmcnt(" #n ")" ::: "memory")
; #define BAR __builtin_amdgcn_s_barrier()
;     ...
;   const int wid = tid >> 6, lane = tid & 63, wr = wid >> 1, wc = wid & 1, fr = lane & 15, fq = lane >> 4;
;   acc_t acc;
; #pragma unroll
;   for (int m = 0; m < 4; ++m)
; #pragma unroll
;     for (int n = 0; n < 4; ++n) acc[m][n] = f32x4{0.f, 0.f, 0.f, 0.f};
;   const int nt = K / BK;
;   unsigned oA0, oA1, oB0, oB1;
;   { int _r, _c; stage_rc(tid * 16, _r, _c); oA0 = _r * lda + _c; oB0 = _r * ldb + _c;
;     stage_rc(tid * 16 + 8192, _r, _c); oA1 = _r * lda + _c; oB1 = _r * ldb + _c; }
;     ...
;     for (int t = 0; t < nt; ++t) {
;       const char* pa = (const char*)SA(b, wr >> 1);
;       const char* pb = (const char*)SB(b);
;       bf16x8 At[4][2], Bf[4][2];
; #pragma unroll
;       for (int m = 0; m < 4; ++m)
; #pragma unroll
;         for (int k = 0; k < 2; ++k) At[m][k] = *reinterpret_cast<const bf16x8*>(pa + lds_byte((wr & 1) * 64 + m * 16 + fr, k * 32 + fq * 8));
; #pragma unroll
;       for (int n = 0; n < 4; ++n)
; #pragma unroll
;         for (int k = 0; k < 2; ++k) Bf[n][k] = *reinterpret_cast<const bf16x8*>(pb + lds_byte(wc * 64 + n * 16 + fr, k * 32 + fq * 8));
;       if (t + 2 < nt) { const int b2 = (b == 0) ? 2 : b - 1; STAGE_ALL(b2, t + 2); WAIT_V(6); } else { WAIT_V(0); }
;       asm volatile("s_waitcnt lgkmcnt(0)" ::: "memory");
;       __builtin_amdgcn_sched_barrier(0);
;       BAR;
;       __builtin_amdgcn_sched_barrier(0);
;       __builtin_amdgcn_s_setprio(1);
; #pragma unroll
;       for (int k = 0; k < 2; ++k)
; #pragma unroll
;         for (int m = 0; m < 4; ++m)
; #pragma unroll
;           for (int n = 0; n < 4; ++n) acc[m][n] = __builtin_amdgcn_mfma_f32_16x16x32_bf16(Bf[n][k], At[m][k], acc[m][n], 0, 0, 0);
.LBB0_107:
	s_or_b64 exec, exec, s[10:11]
	v_lshlrev_b32_e32 v4, 13, v4
	s_ashr_i32 s41, s40, 31
	s_ashr_i32 s39, s38, 31
	v_and_b32_e32 v4, 0xffffc000, v4
	v_lshlrev_b32_e32 v0, 13, v0
	v_and_b32_e32 v8, 15, v133
	v_and_b32_e32 v9, 48, v133
	s_lshl_b64 s[10:11], s[40:41], 11
	s_lshl_b64 s[36:37], s[38:39], 11
	v_lshl_add_u32 v4, v5, 10, v4
	v_and_b32_e32 v0, 0xffffc000, v0
	v_lshl_or_b32 v8, v8, 6, v9
	v_lshlrev_b32_e32 v9, 2, v133
	v_or_b32_e32 v4, v4, v6
	s_add_u32 s36, s59, s36
	v_lshl_add_u32 v0, v1, 10, v0
	v_and_b32_e32 v9, 32, v9
	v_add_u32_sdwa v196, v4, sext(v7) dst_sel:DWORD dst_unused:UNUSED_PAD src0_sel:DWORD src1_sel:WORD_0
	s_addc_u32 s37, s60, s37
	v_or_b32_e32 v0, v0, v2
	v_xad_u32 v8, v8, v9, 16
	v_lshlrev_b32_e32 v9, 6, v133
	v_lshlrev_b32_e32 v10, 7, v133
	v_lshlrev_b64 v[4:5], 1, v[196:197]
	v_add_u32_sdwa v196, v0, sext(v3) dst_sel:DWORD dst_unused:UNUSED_PAD src0_sel:DWORD src1_sel:WORD_0
	s_add_u32 s10, s54, s10
	v_and_b32_e32 v9, 0x2000, v9
	v_and_b32_e32 v10, 0x2000, v10
	v_lshlrev_b64 v[0:1], 1, v[196:197]
	s_addc_u32 s11, s55, s11
	v_mov_b32_e32 v60, 0
	v_ashrrev_i32_e32 v132, 8, v133
	v_add_u32_e32 v129, v8, v9
	v_add_u32_e32 v131, v8, v10
	v_lshl_add_u64 v[134:135], s[36:37], 0, v[4:5]
	v_lshl_add_u64 v[136:137], s[36:37], 0, v[0:1]
	v_lshl_add_u64 v[138:139], s[10:11], 0, v[4:5]
	v_lshl_add_u64 v[140:141], s[10:11], 0, v[0:1]
	s_mov_b32 s39, 0
	s_mov_b64 s[10:11], 0
	s_mov_b32 s41, 0
	v_mov_b32_e32 v61, v60
	v_mov_b32_e32 v62, v60
	v_mov_b32_e32 v63, v60
	v_mov_b32_e32 v56, v60
	v_mov_b32_e32 v57, v60
	v_mov_b32_e32 v58, v60
	v_mov_b32_e32 v59, v60
	v_mov_b32_e32 v52, v60
	v_mov_b32_e32 v53, v60
	v_mov_b32_e32 v54, v60
	v_mov_b32_e32 v55, v60
	v_mov_b32_e32 v48, v60
	v_mov_b32_e32 v49, v60
	v_mov_b32_e32 v50, v60
	v_mov_b32_e32 v51, v60
	v_mov_b32_e32 v44, v60
	v_mov_b32_e32 v45, v60
	v_mov_b32_e32 v46, v60
	v_mov_b32_e32 v47, v60
	v_mov_b32_e32 v40, v60
	v_mov_b32_e32 v41, v60
	v_mov_b32_e32 v42, v60
	v_mov_b32_e32 v43, v60
	v_mov_b32_e32 v36, v60
	v_mov_b32_e32 v37, v60
	v_mov_b32_e32 v38, v60
	v_mov_b32_e32 v39, v60
	v_mov_b32_e32 v32, v60
	v_mov_b32_e32 v33, v60
	v_mov_b32_e32 v34, v60
	v_mov_b32_e32 v35, v60
	v_mov_b32_e32 v28, v60
	v_mov_b32_e32 v29, v60
	v_mov_b32_e32 v30, v60
	v_mov_b32_e32 v31, v60
	v_mov_b32_e32 v24, v60
	v_mov_b32_e32 v25, v60
	v_mov_b32_e32 v26, v60
	v_mov_b32_e32 v27, v60
	v_mov_b32_e32 v20, v60
	v_mov_b32_e32 v21, v60
	v_mov_b32_e32 v22, v60
	v_mov_b32_e32 v23, v60
	v_mov_b32_e32 v16, v60
	v_mov_b32_e32 v17, v60
	v_mov_b32_e32 v18, v60
	v_mov_b32_e32 v19, v60
	v_mov_b32_e32 v12, v60
	v_mov_b32_e32 v13, v60
	v_mov_b32_e32 v14, v60
	v_mov_b32_e32 v15, v60
	v_mov_b32_e32 v8, v60
	v_mov_b32_e32 v9, v60
	v_mov_b32_e32 v10, v60
	v_mov_b32_e32 v11, v60
	v_mov_b32_e32 v4, v60
	v_mov_b32_e32 v5, v60
	v_mov_b32_e32 v6, v60
	v_mov_b32_e32 v7, v60
	v_mov_b32_e32 v0, v60
	v_mov_b32_e32 v1, v60
	v_mov_b32_e32 v2, v60
	v_mov_b32_e32 v3, v60
	v_readfirstlane_b32 s99, v151
	v_lshl_add_u32 v174, v132, 14, v129
	v_mov_b32_e32 v161, v131
	v_lshl_add_u64 v[162:163], v[140:141], 0, s[24:25]
	v_lshl_add_u64 v[164:165], v[138:139], 0, s[24:25]
	v_lshl_add_u64 v[166:167], v[140:141], 0, s[26:27]
	v_lshl_add_u64 v[168:169], v[138:139], 0, s[26:27]
	v_mov_b64_e32 v[170:171], v[136:137]
	v_mov_b64_e32 v[172:173], v[134:135]
	v_mov_b32_e32 v160, v174
	s_add_u32 s98, s99, 0x18000
	s_branch .LBB0_109
.LBB0_108:
	s_waitcnt lgkmcnt(0)
	s_barrier
	s_setprio 1
	s_waitcnt lgkmcnt(0)
	v_mfma_f32_16x16x32_bf16 v[60:63], v[112:115], v[108:111], v[60:63]
	v_mfma_f32_16x16x32_bf16 v[56:59], v[116:119], v[108:111], v[56:59]
	v_mfma_f32_16x16x32_bf16 v[52:55], v[120:123], v[108:111], v[52:55]
	v_mfma_f32_16x16x32_bf16 v[48:51], v[124:127], v[108:111], v[48:51]
	v_mfma_f32_16x16x32_bf16 v[44:47], v[112:115], v[104:107], v[44:47]
	v_mfma_f32_16x16x32_bf16 v[40:43], v[116:119], v[104:107], v[40:43]
	v_mfma_f32_16x16x32_bf16 v[36:39], v[120:123], v[104:107], v[36:39]
	v_mfma_f32_16x16x32_bf16 v[32:35], v[124:127], v[104:107], v[32:35]
	s_cmp_gt_u32 s41, 13
	s_cbranch_scc1 .Lgc3_skd3
	s_add_u32 m0, s98, 0x6000
	s_nop 0
	global_load_lds_dwordx4 v[168:169], off
; #define STAGE_ALL(bufi, kt) do { STAGEA(SA(bufi, 0), brow, kt); STAGEA(SA(bufi, 1), brow + HALF, kt); STAGEB(SB(bufi), bcol, kt); } while (0)
; #define WAIT_V(n) asm volatile("s_waitcnt vmcnt(" #n ")" ::: "memory")
; #define BAR __builtin_amdgcn_s_barrier()
;     ...
;     for (int t = 0; t < nt; ++t) {
;       const char* pa = (const char*)SA(b, wr >> 1);
;       const char* pb = (const char*)SB(b);
;       bf16x8 At[4][2], Bf[4][2];
; #pragma unroll
;       for (int m = 0; m < 4; ++m)
; #pragma unroll
;         for (int k = 0; k < 2; ++k) At[m][k] = *reinterpret_cast<const bf16x8*>(pa + lds_byte((wr & 1) * 64 + m * 16 + fr, k * 32 + fq * 8));
; #pragma unroll
;       for (int n = 0; n < 4; ++n)
; #pragma unroll
;         for (int k = 0; k < 2; ++k) Bf[n][k] = *reinterpret_cast<const bf16x8*>(pb + lds_byte(wc * 64 + n * 16 + fr, k * 32 + fq * 8));
;       if (t + 2 < nt) { const int b2 = (b == 0) ? 2 : b - 1; STAGE_ALL(b2, t + 2); WAIT_V(6); } else { WAIT_V(0); }
;       asm volatile("s_waitcnt lgkmcnt(0)" ::: "memory");
;       __builtin_amdgcn_sched_barrier(0);
;       BAR;
;       __builtin_amdgcn_sched_barrier(0);
;       __builtin_amdgcn_s_setprio(1);
; #pragma unroll
;       for (int k = 0; k < 2; ++k)
; #pragma unroll
;         for (int m = 0; m < 4; ++m)
; #pragma unroll
;           for (int n = 0; n < 4; ++n) acc[m][n] = __builtin_amdgcn_mfma_f32_16x16x32_bf16(Bf[n][k], At[m][k], acc[m][n], 0, 0, 0);
;       __builtin_amdgcn_s_setprio(0);
;       __builtin_amdgcn_sched_barrier(0);
;       BAR;
;       __builtin_amdgcn_sched_barrier(0);
;       b = (b == 2) ? 0 : b + 1;
;     }
.Lgc3_skd3:
	v_mfma_f32_16x16x32_bf16 v[28:31], v[112:115], v[100:103], v[28:31]
	v_mfma_f32_16x16x32_bf16 v[24:27], v[116:119], v[100:103], v[24:27]
	v_mfma_f32_16x16x32_bf16 v[20:23], v[120:123], v[100:103], v[20:23]
	v_mfma_f32_16x16x32_bf16 v[16:19], v[124:127], v[100:103], v[16:19]
	v_mfma_f32_16x16x32_bf16 v[12:15], v[112:115], v[96:99], v[12:15]
	v_mfma_f32_16x16x32_bf16 v[8:11], v[116:119], v[96:99], v[8:11]
	v_mfma_f32_16x16x32_bf16 v[4:7], v[120:123], v[96:99], v[4:7]
	v_mfma_f32_16x16x32_bf16 v[0:3], v[124:127], v[96:99], v[0:3]
	s_cmp_gt_u32 s41, 13
	s_cbranch_scc1 .Lgc3_skd4
	s_add_u32 m0, s98, 0x8000
	s_nop 0
	global_load_lds_dwordx4 v[170:171], off
.Lgc3_skd4:
	v_mfma_f32_16x16x32_bf16 v[60:63], v[80:83], v[76:79], v[60:63]
	v_mfma_f32_16x16x32_bf16 v[56:59], v[84:87], v[76:79], v[56:59]
	v_mfma_f32_16x16x32_bf16 v[52:55], v[88:91], v[76:79], v[52:55]
	v_mfma_f32_16x16x32_bf16 v[48:51], v[92:95], v[76:79], v[48:51]
	v_mfma_f32_16x16x32_bf16 v[44:47], v[80:83], v[72:75], v[44:47]
	v_mfma_f32_16x16x32_bf16 v[40:43], v[84:87], v[72:75], v[40:43]
	v_mfma_f32_16x16x32_bf16 v[36:39], v[88:91], v[72:75], v[36:39]
	v_mfma_f32_16x16x32_bf16 v[32:35], v[92:95], v[72:75], v[32:35]
	s_cmp_gt_u32 s41, 13
	s_cbranch_scc1 .Lgc3_skd5
	s_add_u32 m0, s98, 0xa000
	s_nop 0
	global_load_lds_dwordx4 v[172:173], off
.Lgc3_skd5:
	v_mfma_f32_16x16x32_bf16 v[28:31], v[80:83], v[68:71], v[28:31]
	v_mfma_f32_16x16x32_bf16 v[24:27], v[84:87], v[68:71], v[24:27]
	v_mfma_f32_16x16x32_bf16 v[20:23], v[88:91], v[68:71], v[20:23]
	v_mfma_f32_16x16x32_bf16 v[16:19], v[92:95], v[68:71], v[16:19]
	v_mfma_f32_16x16x32_bf16 v[12:15], v[80:83], v[64:67], v[12:15]
	v_mfma_f32_16x16x32_bf16 v[8:11], v[84:87], v[64:67], v[8:11]
	v_mfma_f32_16x16x32_bf16 v[4:7], v[88:91], v[64:67], v[4:7]
	v_mfma_f32_16x16x32_bf16 v[0:3], v[92:95], v[64:67], v[0:3]
	s_setprio 0
	s_add_i32 s36, s39, 1
	s_cmp_lg_u32 s39, 2
	s_cselect_b32 s39, s36, 0
	s_add_i32 s41, s41, 1
	s_add_u32 s10, s10, 0x80
	s_addc_u32 s11, s11, 0
	s_mul_i32 s36, s39, 0xc000
	v_add_u32_e32 v160, s36, v174
	v_add_u32_e32 v161, s36, v131
	s_mul_i32 s36, s39, 0x6000
	s_addk_i32 s36, 0xa000
	s_cmp_lg_u32 s39, 0
	s_cselect_b32 s36, s36, 0xc000
	s_lshl_b32 s36, s36, 1
	s_add_u32 s98, s36, s99
	v_lshl_add_u64 v[162:163], v[162:163], 0, s[14:15]
	v_lshl_add_u64 v[164:165], v[164:165], 0, s[14:15]
	v_lshl_add_u64 v[166:167], v[166:167], 0, s[14:15]
	v_lshl_add_u64 v[168:169], v[168:169], 0, s[14:15]
	v_lshl_add_u64 v[170:171], v[170:171], 0, s[14:15]
	v_lshl_add_u64 v[172:173], v[172:173], 0, s[14:15]
	s_barrier
	s_cmpk_eq_i32 s10, 0x800
	s_cbranch_scc1 .LBB0_113
.LBB0_109:
	ds_read_b128 v[108:111], v160
	ds_read_b128 v[76:79], v160 offset:1024
	ds_read_b128 v[104:107], v160 offset:2048
	ds_read_b128 v[72:75], v160 offset:3072
	ds_read_b128 v[100:103], v160 offset:4096
	ds_read_b128 v[68:71], v160 offset:5120
	ds_read_b128 v[96:99], v160 offset:6144
	ds_read_b128 v[64:67], v160 offset:7168
	ds_read_b128 v[112:115], v161 offset:32768
	ds_read_b128 v[80:83], v161 offset:33792
	ds_read_b128 v[116:119], v161 offset:34816
	ds_read_b128 v[84:87], v161 offset:35840
	ds_read_b128 v[120:123], v161 offset:36864
	ds_read_b128 v[88:91], v161 offset:37888
	ds_read_b128 v[124:127], v161 offset:38912
	ds_read_b128 v[92:95], v161 offset:39936
	s_cmp_gt_u32 s41, 13
	s_cbranch_scc1 .Lgc3_nostage
	s_mov_b32 m0, s98
	s_nop 0
	global_load_lds_dwordx4 v[162:163], off
	s_add_u32 m0, s98, 0x2000
	s_nop 0
	global_load_lds_dwordx4 v[164:165], off
	s_add_u32 m0, s98, 0x4000
	s_nop 0
	global_load_lds_dwordx4 v[166:167], off
	s_waitcnt vmcnt(3)
	s_branch .LBB0_108

; DI unsigned pack2(float a, float b) { f32x2_t v = {a, b}; bf16x2_t r = __builtin_convertvector(v, bf16x2_t); return __builtin_bit_cast(unsigned, r); }
; #define LOADT(key0) do { kr0 = *(const uint4*)(Kp + (size_t)((key0) + krow0) * ldk + kch0 * 8); \
;     if (k2) kr1 = *(const uint4*)(Kp + (size_t)((key0) + krow1) * ldk + kch1 * 8); \
;     vr = *(const uint4*)(Vt + (size_t)vrow * S_ + (key0) + vch * 8); } while (0)
; template <int D>
; DI void attn_tile(const u16* __restrict__ Qp, int ldq, const u16* __restrict__ Kp, int ldk, const u16* __restrict__ Vt,
;                   u16* __restrict__ Op, int ldo, int q0, float cs, float mc) {
;     ...
;   f32x16 o0, o1, s0, s1;
; #pragma unroll
;   for (int i = 0; i < 16; ++i) { o0[i] = 0.f; o1[i] = 0.f; }
;   float lsum0 = 0.f, lsum1 = 0.f;
;   uint4 kr0, kr1, vr;
;   const int vrow = tid >> 3, vch = tid & 7;
;   int krow0, kch0, krow1 = 0, kch1 = 0;
;   if (D == 64) { krow0 = tid >> 3; kch0 = tid & 7; }
;   else { krow0 = tid / CPR; kch0 = tid % CPR; int i2 = tid + 512; krow1 = i2 / CPR; kch1 = i2 % CPR; }
;   const bool k2 = (D == 96) && (tid < 256);
;   kr1 = uint4{0, 0, 0, 0};
;     ...
;   bf16x8 kf0[NKS], kf1[NKS];
;   LOADT(0); STORET(0);
;   LOADT(64); STORET(1);
;   __syncthreads();
;   LOADT(128);
;   LOADKF(0);
;   SMMA();
;   if (grp == 1) BARX;
; #pragma unroll 1
;   for (int it = 0; it < NIT; ++it) {
;     bf16x8 pf[2][2];
;     if (mc != 0.f) {
; #pragma unroll
;       for (int i = 0; i < 16; ++i) { s0[i] -= mc; s1[i] -= mc; }
;     }
; #pragma unroll
;     for (int i = 0; i < 16; ++i) {
;       s0[i] = __builtin_amdgcn_exp2f(s0[i]); s1[i] = __builtin_amdgcn_exp2f(s1[i]);
;       lsum0 += s0[i]; lsum1 += s1[i];
;     }
; #pragma unroll
;     for (int st = 0; st < 2; ++st) {
;       uint4 a = {pack2(s0[8 * st], s0[8 * st + 1]), pack2(s0[8 * st + 2], s0[8 * st + 3]), pack2(s0[8 * st + 4], s0[8 * st + 5]), pack2(s0[8 * st + 6], s0[8 * st + 7])};
;       uint4 c = {pack2(s1[8 * st], s1[8 * st + 1]), pack2(s1[8 * st + 2], s1[8 * st + 3]), pack2(s1[8 * st + 4], s1[8 * st + 5]), pack2(s1[8 * st + 6], s1[8 * st + 7])};
;       pf[0][st] = __builtin_bit_cast(bf16x8, a); pf[1][st] = __builtin_bit_cast(bf16x8, c);
;     }
;     if (it + 2 < NIT) STORET((it + 2) & 3);
.LBB0_185:
	s_or_b64 exec, exec, s[44:45]
	s_lshr_b32 s37, s60, 6
	s_and_b32 s37, s37, 7
	s_add_i32 s36, s36, s37
	s_lshl_b32 s44, s37, 8
	s_ashr_i32 s37, s36, 31
	v_mul_u32_u24_e32 v0, 0x90, v24
	s_lshl_b64 s[36:37], s[36:37], 21
	v_add3_u32 v196, 16, v0, v196
	v_lshl_add_u64 v[0:1], s[36:37], 0, v[16:17]
	v_mov_b32_e32 v201, v197
	v_lshl_add_u64 v[0:1], v[0:1], 0, v[200:201]
	s_add_u32 s10, s44, s10
	v_lshl_add_u64 v[202:203], s[2:3], 0, v[0:1]
	v_lshlrev_b64 v[0:1], 11, v[12:13]
	s_addc_u32 s11, 0, s11
	v_lshl_add_u64 v[0:1], s[10:11], 0, v[0:1]
	v_lshl_add_u64 v[0:1], v[14:15], 1, v[0:1]
	v_lshl_add_u64 v[204:205], s[8:9], 0, v[0:1]
	v_lshl_add_u64 v[0:1], s[10:11], 0, v[8:9]
	v_lshl_add_u64 v[0:1], v[10:11], 1, v[0:1]
	v_lshl_add_u64 v[206:207], s[8:9], 0, v[0:1]
	v_mov_b32_e32 v0, 0
	v_and_b32_e32 v250, 63, v234
	v_ashrrev_i32_e32 v199, 31, v198
	s_mov_b32 s37, 0
	v_mov_b32_e32 v1, v0
	v_mov_b32_e32 v2, v0
	v_mov_b32_e32 v3, v0
	v_mov_b32_e32 v4, v0
	v_mov_b32_e32 v5, v0
	v_mov_b32_e32 v6, v0
	v_mov_b32_e32 v7, v0
	v_mov_b32_e32 v8, v0
	v_mov_b32_e32 v9, v0
	v_mov_b32_e32 v10, v0
	v_mov_b32_e32 v11, v0
	v_mov_b32_e32 v12, v0
	v_mov_b32_e32 v13, v0
	v_mov_b32_e32 v14, v0
	v_mov_b32_e32 v15, v0
	v_mov_b32_e32 v16, v0
	v_mov_b32_e32 v17, v0
	v_mov_b32_e32 v18, v0
	v_mov_b32_e32 v19, v0
	v_mov_b32_e32 v20, v0
	v_mov_b32_e32 v21, v0
	v_mov_b32_e32 v22, v0
	v_mov_b32_e32 v23, v0
	v_mov_b32_e32 v24, v0
	v_mov_b32_e32 v25, v0
	v_mov_b32_e32 v26, v0
	v_mov_b32_e32 v27, v0
	v_mov_b32_e32 v28, v0
	v_mov_b32_e32 v29, v0
	v_mov_b32_e32 v30, v0
	v_mov_b32_e32 v31, v0
	v_mov_b32_e32 v208, v0
	v_mov_b32_e32 v209, v0
	s_andn2_b64 vcc, exec, s[38:39]
	s_cbranch_vccnz .Lat96_p0
	v_sub_f32_e32 v47, v47, v232
	v_sub_f32_e32 v46, v46, v232
	v_sub_f32_e32 v45, v45, v232
	v_sub_f32_e32 v44, v44, v232
	v_sub_f32_e32 v43, v43, v232
	v_sub_f32_e32 v42, v42, v232
	v_sub_f32_e32 v41, v41, v232
	v_sub_f32_e32 v40, v40, v232
	v_sub_f32_e32 v39, v39, v232
	v_sub_f32_e32 v38, v38, v232
	v_sub_f32_e32 v37, v37, v232
	v_sub_f32_e32 v36, v36, v232
	v_sub_f32_e32 v35, v35, v232
	v_sub_f32_e32 v34, v34, v232
	v_sub_f32_e32 v33, v33, v232
	v_sub_f32_e32 v32, v32, v232
	v_sub_f32_e32 v63, v63, v232
	v_sub_f32_e32 v62, v62, v232
	v_sub_f32_e32 v61, v61, v232
	v_sub_f32_e32 v60, v60, v232
	v_sub_f32_e32 v59, v59, v232
	v_sub_f32_e32 v58, v58, v232
	v_sub_f32_e32 v57, v57, v232
	v_sub_f32_e32 v56, v56, v232
	v_sub_f32_e32 v55, v55, v232
	v_sub_f32_e32 v54, v54, v232
	v_sub_f32_e32 v53, v53, v232
	v_sub_f32_e32 v52, v52, v232
	v_sub_f32_e32 v51, v51, v232
	v_sub_f32_e32 v50, v50, v232
	v_sub_f32_e32 v49, v49, v232
	v_sub_f32_e32 v48, v48, v232
.Lat96_p0:
	v_exp_f32_e32 v64, v32
	v_exp_f32_e32 v80, v48
	v_exp_f32_e32 v65, v33
	v_exp_f32_e32 v81, v49
	v_exp_f32_e32 v66, v34
	v_exp_f32_e32 v82, v50
	v_exp_f32_e32 v67, v35
	v_exp_f32_e32 v83, v51
	v_exp_f32_e32 v68, v36
	v_exp_f32_e32 v84, v52
	v_exp_f32_e32 v69, v37
	v_exp_f32_e32 v85, v53
	v_exp_f32_e32 v70, v38
	v_exp_f32_e32 v86, v54
	v_exp_f32_e32 v71, v39
	v_exp_f32_e32 v87, v55
	v_exp_f32_e32 v72, v40
	v_exp_f32_e32 v88, v56
	v_exp_f32_e32 v73, v41
	v_exp_f32_e32 v89, v57
	v_exp_f32_e32 v74, v42
	v_exp_f32_e32 v90, v58
	v_exp_f32_e32 v75, v43
	v_exp_f32_e32 v91, v59
	v_exp_f32_e32 v76, v44
	v_exp_f32_e32 v92, v60
	v_exp_f32_e32 v77, v45
	v_exp_f32_e32 v93, v61
	v_exp_f32_e32 v78, v46
	v_exp_f32_e32 v94, v62
	v_exp_f32_e32 v79, v47
	v_exp_f32_e32 v95, v63
.LBB0_188:
	s_add_i32 s36, s37, 1
	s_cmpk_gt_u32 s37, 0xfd
	s_cbranch_scc1 .LBB0_194
	s_and_b32 s10, s37, 3
	s_xor_b32 s10, s10, 2
	s_mulk_i32 s10, 0x5800
	s_add_i32 s45, s10, 16
	v_add3_u32 v227, s45, v235, v245
	s_waitcnt vmcnt(1)
	ds_write_b128 v227, v[124:127]
	s_and_saveexec_b64 s[10:11], s[40:41]
	v_add3_u32 v227, s45, v246, v247
	ds_write_b128 v227, v[120:123]
	s_or_b64 exec, exec, s[10:11]
	v_add3_u32 v227, s45, v248, v200
	s_waitcnt vmcnt(0)
	ds_write_b128 v227, v[136:139] offset:13312

; #define LOADT(key0) do { kr0 = *(const uint4*)(Kp + (size_t)((key0) + krow0) * ldk + kch0 * 8); \
;     if (k2) kr1 = *(const uint4*)(Kp + (size_t)((key0) + krow1) * ldk + kch1 * 8); \
;     vr = *(const uint4*)(Vt + (size_t)vrow * S_ + (key0) + vch * 8); } while (0)
; #define STORET(bufi) do { char* bb = smem + (bufi) * BUF; *(uint4*)(bb + krow0 * KS + kch0 * 16) = kr0; \
;     if (k2) *(uint4*)(bb + krow1 * KS + kch1 * 16) = kr1; \
;     *(uint4*)(bb + KB + vrow * VS + vch * 16) = vr; } while (0)
; #define LOADKF(bufi) do { const char* kb_ = smem + (bufi) * BUF + r * KS + 16 * hh; \
;     _Pragma("unroll") for (int ks = 0; ks < NKS; ++ks) { kf0[ks] = *(const bf16x8*)(kb_ + 32 * ks); kf1[ks] = *(const bf16x8*)(kb_ + 32 * KS + 32 * ks); } } while (0)
; #define BARX do { __builtin_amdgcn_sched_barrier(0); asm volatile("s_waitcnt lgkmcnt(0)" ::: "memory"); __builtin_amdgcn_s_barrier(); __builtin_amdgcn_sched_barrier(0); } while (0)
; template <int D>
; DI void attn_tile(const u16* __restrict__ Qp, int ldq, const u16* __restrict__ Kp, int ldk, const u16* __restrict__ Vt,
;                   u16* __restrict__ Op, int ldo, int q0, float cs, float mc) {
;     ...
;     if (it + 2 < NIT) STORET((it + 2) & 3);
;     if (it + 3 < NIT) LOADT((it + 3) * 64);
;     if (it + 1 < NIT) LOADKF((it + 1) & 3);
;     BARX;
;     __builtin_amdgcn_s_setprio(1);
;     {
;       const char* vb = smem + (it & 3) * BUF + KB + r * VS + 16 * hh;
;       bf16x8 v0[2], v1[2];
; #pragma unroll
;       for (int q = 0; q < 2; ++q) { v0[q] = *(const bf16x8*)(vb + 32 * q); v1[q] = *(const bf16x8*)(vb + 32 * VS + 32 * q); }
;       if (it + 1 < NIT) SMMA();
; #pragma unroll
;       for (int q = 0; q < 2; ++q) {
;         o0 = __builtin_amdgcn_mfma_f32_32x32x16_bf16(v0[q], pf[0][q], o0, 0, 0, 0);
;         o1 = __builtin_amdgcn_mfma_f32_32x32x16_bf16(v1[q], pf[0][q], o1, 0, 0, 0);
;       }
; #pragma unroll
;       for (int q = 0; q < 2; ++q) { v0[q] = *(const bf16x8*)(vb + 64 + 32 * q); v1[q] = *(const bf16x8*)(vb + 32 * VS + 64 + 32 * q); }
; #pragma unroll
;       for (int q = 0; q < 2; ++q) {
;         o0 = __builtin_amdgcn_mfma_f32_32x32x16_bf16(v0[q], pf[1][q], o0, 0, 0, 0);
;         o1 = __builtin_amdgcn_mfma_f32_32x32x16_bf16(v1[q], pf[1][q], o1, 0, 0, 0);
;       }
;     }
;     __builtin_amdgcn_s_setprio(0);
;     BARX;
.LBB0_197:
	s_or_b64 exec, exec, s[10:11]
	global_load_dwordx4 v[136:139], v[202:203], off
	v_lshl_add_u64 v[202:203], v[202:203], 0, s[14:15]
	v_lshl_add_u64 v[204:205], v[204:205], 0, s[30:31]
	v_lshl_add_u64 v[206:207], v[206:207], 0, s[30:31]
.LBB0_198:
	s_and_b32 s44, s36, 3
	s_mulk_i32 s44, 0x5800
	v_add_u32_e32 v226, s44, v249
	ds_read_b128 v[128:131], v226
	ds_read_b128 v[132:135], v226 offset:32
	ds_read_b128 v[140:143], v226 offset:6656
	ds_read_b128 v[144:147], v226 offset:6688
	ds_read_b128 v[148:151], v226 offset:64
	ds_read_b128 v[152:155], v226 offset:96
	ds_read_b128 v[156:159], v226 offset:6720
	ds_read_b128 v[160:163], v226 offset:6752
	ds_read_b128 v[164:167], v226 offset:128
	ds_read_b128 v[168:171], v226 offset:160
	ds_read_b128 v[172:175], v226 offset:6784
	ds_read_b128 v[176:179], v226 offset:6816
	s_waitcnt lgkmcnt(0)
	s_barrier
	s_setprio 1
	s_and_b32 s10, s37, 3
	s_mulk_i32 s10, 0x5800
	v_add_u32_e32 v201, s10, v196
	v_mfma_f32_32x32x16_bf16 v[32:47], v[128:131], v[96:99], 0
	ds_read_b128 v[188:191], v201 offset:13312
	ds_read_b128 v[192:195], v201 offset:17920
	v_cvt_pk_bf16_f32 v210, v64, v65
	v_cvt_pk_bf16_f32 v211, v66, v67
	v_cvt_pk_bf16_f32 v212, v68, v69
	v_cvt_pk_bf16_f32 v213, v70, v71
	v_mfma_f32_32x32x16_bf16 v[48:63], v[140:143], v[96:99], 0
	ds_read_b128 v[184:187], v201 offset:13344
	ds_read_b128 v[180:183], v201 offset:17952
	v_cvt_pk_bf16_f32 v214, v72, v73
	v_cvt_pk_bf16_f32 v215, v74, v75
	v_cvt_pk_bf16_f32 v216, v76, v77
	v_cvt_pk_bf16_f32 v217, v78, v79
	v_mfma_f32_32x32x16_bf16 v[32:47], v[132:135], v[100:103], v[32:47]
	v_cvt_pk_bf16_f32 v218, v80, v81
	v_cvt_pk_bf16_f32 v219, v82, v83
	v_cvt_pk_bf16_f32 v220, v84, v85
	v_cvt_pk_bf16_f32 v221, v86, v87
	v_mfma_f32_32x32x16_bf16 v[48:63], v[144:147], v[100:103], v[48:63]
	v_cvt_pk_bf16_f32 v222, v88, v89
	v_cvt_pk_bf16_f32 v223, v90, v91
	v_cvt_pk_bf16_f32 v224, v92, v93
	v_cvt_pk_bf16_f32 v225, v94, v95
	v_mfma_f32_32x32x16_bf16 v[32:47], v[148:151], v[104:107], v[32:47]
	v_add_f32_e32 v208, v64, v208
	v_add_f32_e32 v209, v80, v209
	v_add_f32_e32 v208, v65, v208
	v_add_f32_e32 v209, v81, v209
	v_mfma_f32_32x32x16_bf16 v[48:63], v[156:159], v[104:107], v[48:63]
	v_add_f32_e32 v208, v66, v208
	v_add_f32_e32 v209, v82, v209
	v_add_f32_e32 v208, v67, v208
	v_add_f32_e32 v209, v83, v209
	v_mfma_f32_32x32x16_bf16 v[32:47], v[152:155], v[108:111], v[32:47]
	v_add_f32_e32 v208, v68, v208
	v_add_f32_e32 v209, v84, v209
	v_add_f32_e32 v208, v69, v208
	v_add_f32_e32 v209, v85, v209
	v_mfma_f32_32x32x16_bf16 v[48:63], v[160:163], v[108:111], v[48:63]
	v_add_f32_e32 v208, v70, v208
	v_add_f32_e32 v209, v86, v209
	v_add_f32_e32 v208, v71, v208
	v_add_f32_e32 v209, v87, v209
	v_mfma_f32_32x32x16_bf16 v[32:47], v[164:167], v[112:115], v[32:47]
	v_add_f32_e32 v208, v72, v208
	v_add_f32_e32 v209, v88, v209
	v_add_f32_e32 v208, v73, v208
	v_add_f32_e32 v209, v89, v209
	v_mfma_f32_32x32x16_bf16 v[48:63], v[172:175], v[112:115], v[48:63]
	v_add_f32_e32 v208, v74, v208
	v_add_f32_e32 v209, v90, v209
	v_add_f32_e32 v208, v75, v208
	v_add_f32_e32 v209, v91, v209
	v_mfma_f32_32x32x16_bf16 v[32:47], v[168:171], v[116:119], v[32:47]
	v_add_f32_e32 v208, v76, v208
	v_add_f32_e32 v209, v92, v209
	v_add_f32_e32 v208, v77, v208
	v_add_f32_e32 v209, v93, v209
	v_mfma_f32_32x32x16_bf16 v[48:63], v[176:179], v[116:119], v[48:63]
	v_add_f32_e32 v208, v78, v208
	v_add_f32_e32 v209, v94, v209
	v_add_f32_e32 v208, v79, v208
	v_add_f32_e32 v209, v95, v209
	ds_read_b128 v[140:143], v201 offset:13376
	ds_read_b128 v[144:147], v201 offset:17984
	ds_read_b128 v[148:151], v201 offset:13408
	ds_read_b128 v[152:155], v201 offset:18016
	s_andn2_b64 vcc, exec, s[38:39]
	s_cbranch_vccnz .LBB0_190
	s_nop 3
	v_sub_f32_e32 v47, v47, v232
	v_sub_f32_e32 v46, v46, v232
	v_sub_f32_e32 v45, v45, v232
	v_sub_f32_e32 v44, v44, v232
	v_sub_f32_e32 v43, v43, v232
	v_sub_f32_e32 v42, v42, v232
	v_sub_f32_e32 v41, v41, v232
	v_sub_f32_e32 v40, v40, v232
	v_sub_f32_e32 v39, v39, v232
	v_sub_f32_e32 v38, v38, v232
	v_sub_f32_e32 v37, v37, v232
	v_sub_f32_e32 v36, v36, v232
	v_sub_f32_e32 v35, v35, v232
	v_sub_f32_e32 v34, v34, v232
	v_sub_f32_e32 v33, v33, v232
	v_sub_f32_e32 v32, v32, v232
	v_sub_f32_e32 v63, v63, v232
	v_sub_f32_e32 v62, v62, v232
	v_sub_f32_e32 v61, v61, v232
	v_sub_f32_e32 v60, v60, v232
	v_sub_f32_e32 v59, v59, v232
	v_sub_f32_e32 v58, v58, v232
	v_sub_f32_e32 v57, v57, v232
	v_sub_f32_e32 v56, v56, v232
	v_sub_f32_e32 v55, v55, v232
	v_sub_f32_e32 v54, v54, v232
	v_sub_f32_e32 v53, v53, v232
	v_sub_f32_e32 v52, v52, v232
	v_sub_f32_e32 v51, v51, v232
	v_sub_f32_e32 v50, v50, v232
	v_sub_f32_e32 v49, v49, v232
	v_sub_f32_e32 v48, v48, v232
.LBB0_190:
	s_waitcnt lgkmcnt(7)
	v_mfma_f32_32x32x16_bf16 v[0:15], v[188:191], v[210:213], v[0:15]
	v_exp_f32_e32 v64, v32
	v_exp_f32_e32 v65, v33
	v_exp_f32_e32 v66, v34
	v_exp_f32_e32 v67, v35
	s_waitcnt lgkmcnt(6)
	v_mfma_f32_32x32x16_bf16 v[16:31], v[192:195], v[210:213], v[16:31]
	v_exp_f32_e32 v68, v36
	v_exp_f32_e32 v69, v37
	v_exp_f32_e32 v70, v38
	v_exp_f32_e32 v71, v39
	s_waitcnt lgkmcnt(5)
	v_mfma_f32_32x32x16_bf16 v[0:15], v[184:187], v[214:217], v[0:15]
	v_exp_f32_e32 v72, v40
	v_exp_f32_e32 v73, v41
	v_exp_f32_e32 v74, v42
	v_exp_f32_e32 v75, v43
	s_waitcnt lgkmcnt(4)
	v_mfma_f32_32x32x16_bf16 v[16:31], v[180:183], v[214:217], v[16:31]
	v_exp_f32_e32 v76, v44
	v_exp_f32_e32 v77, v45
	v_exp_f32_e32 v78, v46
	v_exp_f32_e32 v79, v47
	s_waitcnt lgkmcnt(3)
	v_mfma_f32_32x32x16_bf16 v[0:15], v[140:143], v[218:221], v[0:15]
	v_exp_f32_e32 v80, v48
	v_exp_f32_e32 v81, v49
	v_exp_f32_e32 v82, v50
	v_exp_f32_e32 v83, v51
	s_waitcnt lgkmcnt(2)
	v_mfma_f32_32x32x16_bf16 v[16:31], v[144:147], v[218:221], v[16:31]
	v_exp_f32_e32 v84, v52
	v_exp_f32_e32 v85, v53
	v_exp_f32_e32 v86, v54
	v_exp_f32_e32 v87, v55
	s_waitcnt lgkmcnt(1)
	v_mfma_f32_32x32x16_bf16 v[0:15], v[148:151], v[222:225], v[0:15]
	v_exp_f32_e32 v88, v56
	v_exp_f32_e32 v89, v57
	v_exp_f32_e32 v90, v58
	v_exp_f32_e32 v91, v59
	s_waitcnt lgkmcnt(0)
	v_mfma_f32_32x32x16_bf16 v[16:31], v[152:155], v[222:225], v[16:31]
	v_exp_f32_e32 v92, v60
	v_exp_f32_e32 v93, v61
	v_exp_f32_e32 v94, v62
	v_exp_f32_e32 v95, v63
	s_setprio 0
	s_barrier
	s_cmpk_eq_i32 s36, 0x100
	s_mov_b32 s37, s36
	s_cbranch_scc0 .LBB0_188

; #define LOADT(key0) do { kr0 = *(const uint4*)(Kp + (size_t)((key0) + krow0) * ldk + kch0 * 8); \
;     if (k2) kr1 = *(const uint4*)(Kp + (size_t)((key0) + krow1) * ldk + kch1 * 8); \
;     vr = *(const uint4*)(Vt + (size_t)vrow * S_ + (key0) + vch * 8); } while (0)
; #define STORET(bufi) do { char* bb = smem + (bufi) * BUF; *(uint4*)(bb + krow0 * KS + kch0 * 16) = kr0; \
;     if (k2) *(uint4*)(bb + krow1 * KS + kch1 * 16) = kr1; \
;     *(uint4*)(bb + KB + vrow * VS + vch * 16) = vr; } while (0)
; #define LOADKF(bufi) do { const char* kb_ = smem + (bufi) * BUF + r * KS + 16 * hh; \
;     _Pragma("unroll") for (int ks = 0; ks < NKS; ++ks) { kf0[ks] = *(const bf16x8*)(kb_ + 32 * ks); kf1[ks] = *(const bf16x8*)(kb_ + 32 * KS + 32 * ks); } } while (0)
; #define BARX do { __builtin_amdgcn_sched_barrier(0); asm volatile("s_waitcnt lgkmcnt(0)" ::: "memory"); __builtin_amdgcn_s_barrier(); __builtin_amdgcn_sched_barrier(0); } while (0)
; template <int D>
; DI void attn_tile(const u16* __restrict__ Qp, int ldq, const u16* __restrict__ Kp, int ldk, const u16* __restrict__ Vt,
;                   u16* __restrict__ Op, int ldo, int q0, float cs, float mc) {
;     ...
;   f32x16 o0, o1, s0, s1;
; #pragma unroll
;   for (int i = 0; i < 16; ++i) { o0[i] = 0.f; o1[i] = 0.f; }
;   float lsum0 = 0.f, lsum1 = 0.f;
;   uint4 kr0, kr1, vr;
;   const int vrow = tid >> 3, vch = tid & 7;
;   int krow0, kch0, krow1 = 0, kch1 = 0;
;   if (D == 64) { krow0 = tid >> 3; kch0 = tid & 7; }
;   else { krow0 = tid / CPR; kch0 = tid % CPR; int i2 = tid + 512; krow1 = i2 / CPR; kch1 = i2 % CPR; }
;   const bool k2 = (D == 96) && (tid < 256);
;   kr1 = uint4{0, 0, 0, 0};
;     ...
;   bf16x8 kf0[NKS], kf1[NKS];
;   LOADT(0); STORET(0);
;   LOADT(64); STORET(1);
;   __syncthreads();
;   LOADT(128);
;   LOADKF(0);
;   SMMA();
;   if (grp == 1) BARX;
; #pragma unroll 1
;   for (int it = 0; it < NIT; ++it) {
;     bf16x8 pf[2][2];
;     if (mc != 0.f) {
; #pragma unroll
;       for (int i = 0; i < 16; ++i) { s0[i] -= mc; s1[i] -= mc; }
;     }
; #pragma unroll
;     for (int i = 0; i < 16; ++i) {
;       s0[i] = __builtin_amdgcn_exp2f(s0[i]); s1[i] = __builtin_amdgcn_exp2f(s1[i]);
;       lsum0 += s0[i]; lsum1 += s1[i];
;     }
.LBB0_827:
	s_or_b64 exec, exec, s[40:41]
	s_lshr_b32 s37, s46, 8
	s_and_b32 s37, s37, 1
	s_lshl_b32 s40, s37, 7
	s_add_u32 s10, s40, s10
	s_addc_u32 s11, 0, s11
	v_lshl_add_u64 v[2:3], s[10:11], 0, v[2:3]
	s_add_i32 s10, s36, s37
	s_ashr_i32 s11, s10, 31
	v_and_b32_e32 v4, 7, v202
	s_lshl_b64 s[10:11], s[10:11], 21
	v_lshlrev_b32_e32 v196, 4, v4
	v_lshl_add_u64 v[0:1], s[10:11], 0, v[0:1]
	v_lshl_add_u64 v[0:1], v[0:1], 0, v[196:197]
	v_lshl_add_u64 v[2:3], v[2:3], 0, v[196:197]
	v_lshl_add_u64 v[172:173], s[8:9], 0, v[0:1]
	v_mov_b32_e32 v0, 0
	v_and_b32_e32 v205, 63, v202
	v_lshl_add_u64 v[170:171], s[2:3], 0, v[2:3]
	s_mov_b32 s37, 0
	v_mov_b32_e32 v1, v0
	v_mov_b32_e32 v2, v0
	v_mov_b32_e32 v3, v0
	v_mov_b32_e32 v4, v0
	v_mov_b32_e32 v5, v0
	v_mov_b32_e32 v6, v0
	v_mov_b32_e32 v7, v0
	v_mov_b32_e32 v8, v0
	v_mov_b32_e32 v9, v0
	v_mov_b32_e32 v10, v0
	v_mov_b32_e32 v11, v0
	v_mov_b32_e32 v12, v0
	v_mov_b32_e32 v13, v0
	v_mov_b32_e32 v14, v0
	v_mov_b32_e32 v15, v0
	v_mov_b32_e32 v16, v0
	v_mov_b32_e32 v17, v0
	v_mov_b32_e32 v18, v0
	v_mov_b32_e32 v19, v0
	v_mov_b32_e32 v20, v0
	v_mov_b32_e32 v21, v0
	v_mov_b32_e32 v22, v0
	v_mov_b32_e32 v23, v0
	v_mov_b32_e32 v24, v0
	v_mov_b32_e32 v25, v0
	v_mov_b32_e32 v26, v0
	v_mov_b32_e32 v27, v0
	v_mov_b32_e32 v28, v0
	v_mov_b32_e32 v29, v0
	v_mov_b32_e32 v30, v0
	v_mov_b32_e32 v31, v0
	v_mov_b32_e32 v174, v0
	v_mov_b32_e32 v175, v0
	s_andn2_b64 vcc, exec, s[38:39]
	s_cbranch_vccnz .Lat64_p0
	v_sub_f32_e32 v47, v47, v200
	v_sub_f32_e32 v46, v46, v200
	v_sub_f32_e32 v45, v45, v200
	v_sub_f32_e32 v44, v44, v200
	v_sub_f32_e32 v43, v43, v200
	v_sub_f32_e32 v42, v42, v200
	v_sub_f32_e32 v41, v41, v200
	v_sub_f32_e32 v40, v40, v200
	v_sub_f32_e32 v39, v39, v200
	v_sub_f32_e32 v38, v38, v200
	v_sub_f32_e32 v37, v37, v200
	v_sub_f32_e32 v36, v36, v200
	v_sub_f32_e32 v35, v35, v200
	v_sub_f32_e32 v34, v34, v200
	v_sub_f32_e32 v33, v33, v200
	v_sub_f32_e32 v32, v32, v200
	v_sub_f32_e32 v63, v63, v200
	v_sub_f32_e32 v62, v62, v200
	v_sub_f32_e32 v61, v61, v200
	v_sub_f32_e32 v60, v60, v200
	v_sub_f32_e32 v59, v59, v200
	v_sub_f32_e32 v58, v58, v200
	v_sub_f32_e32 v57, v57, v200
	v_sub_f32_e32 v56, v56, v200
	v_sub_f32_e32 v55, v55, v200
	v_sub_f32_e32 v54, v54, v200
	v_sub_f32_e32 v53, v53, v200
	v_sub_f32_e32 v52, v52, v200
	v_sub_f32_e32 v51, v51, v200
	v_sub_f32_e32 v50, v50, v200
	v_sub_f32_e32 v49, v49, v200
	v_sub_f32_e32 v48, v48, v200

; DI unsigned pack2(float a, float b) { f32x2_t v = {a, b}; bf16x2_t r = __builtin_convertvector(v, bf16x2_t); return __builtin_bit_cast(unsigned, r); }
; template <int D>
; DI void attn_tile(const u16* __restrict__ Qp, int ldq, const u16* __restrict__ Kp, int ldk, const u16* __restrict__ Vt,
;                   u16* __restrict__ Op, int ldo, int q0, float cs, float mc) {
;     ...
;     if (mc != 0.f) {
; #pragma unroll
;       for (int i = 0; i < 16; ++i) { s0[i] -= mc; s1[i] -= mc; }
;     }
; #pragma unroll
;     for (int i = 0; i < 16; ++i) {
;       s0[i] = __builtin_amdgcn_exp2f(s0[i]); s1[i] = __builtin_amdgcn_exp2f(s1[i]);
;       lsum0 += s0[i]; lsum1 += s1[i];
;     }
; #pragma unroll
;     for (int st = 0; st < 2; ++st) {
;       uint4 a = {pack2(s0[8 * st], s0[8 * st + 1]), pack2(s0[8 * st + 2], s0[8 * st + 3]), pack2(s0[8 * st + 4], s0[8 * st + 5]), pack2(s0[8 * st + 6], s0[8 * st + 7])};
;       uint4 c = {pack2(s1[8 * st], s1[8 * st + 1]), pack2(s1[8 * st + 2], s1[8 * st + 3]), pack2(s1[8 * st + 4], s1[8 * st + 5]), pack2(s1[8 * st + 6], s1[8 * st + 7])};
;       pf[0][st] = __builtin_bit_cast(bf16x8, a); pf[1][st] = __builtin_bit_cast(bf16x8, c);
;     }
;     if (it + 2 < NIT) STORET((it + 2) & 3);
;     if (it + 3 < NIT) LOADT((it + 3) * 64);
;     if (it + 1 < NIT) LOADKF((it + 1) & 3);
;     BARX;
;     __builtin_amdgcn_s_setprio(1);
;     {
;       const char* vb = smem + (it & 3) * BUF + KB + r * VS + 16 * hh;
;       bf16x8 v0[2], v1[2];
; #pragma unroll
;       for (int q = 0; q < 2; ++q) { v0[q] = *(const bf16x8*)(vb + 32 * q); v1[q] = *(const bf16x8*)(vb + 32 * VS + 32 * q); }
;       if (it + 1 < NIT) SMMA();
; #pragma unroll
;       for (int q = 0; q < 2; ++q) {
;         o0 = __builtin_amdgcn_mfma_f32_32x32x16_bf16(v0[q], pf[0][q], o0, 0, 0, 0);
;         o1 = __builtin_amdgcn_mfma_f32_32x32x16_bf16(v1[q], pf[0][q], o1, 0, 0, 0);
;       }
; #pragma unroll
;       for (int q = 0; q < 2; ++q) { v0[q] = *(const bf16x8*)(vb + 64 + 32 * q); v1[q] = *(const bf16x8*)(vb + 32 * VS + 64 + 32 * q); }
; #pragma unroll
;       for (int q = 0; q < 2; ++q) {
;         o0 = __builtin_amdgcn_mfma_f32_32x32x16_bf16(v0[q], pf[1][q], o0, 0, 0, 0);
;         o1 = __builtin_amdgcn_mfma_f32_32x32x16_bf16(v1[q], pf[1][q], o1, 0, 0, 0);
;       }
;     }
;     __builtin_amdgcn_s_setprio(0);
;     BARX;
.LBB0_830:
	s_add_i32 s36, s37, 1
	s_cmpk_gt_u32 s37, 0xfd
	s_cbranch_scc1 .LBB0_834
	s_and_b32 s10, s37, 3
	s_xor_b32 s10, s10, 2
	s_mulk_i32 s10, 0x4800
	v_add_u32_e32 v193, s10, v203
	s_waitcnt vmcnt(1)
	ds_write_b128 v193, v[112:115]
	s_waitcnt vmcnt(0)
	ds_write_b128 v193, v[116:119] offset:9216
.LBB0_834:
	s_cmpk_gt_u32 s37, 0xfc
	s_cbranch_scc1 .LBB0_836
	global_load_dwordx4 v[112:115], v[170:171], off
	global_load_dwordx4 v[116:119], v[172:173], off
	s_mov_b64 s[10:11], 0x80000
	v_lshl_add_u64 v[170:171], v[170:171], 0, s[10:11]
	v_lshl_add_u64 v[172:173], v[172:173], 0, s[14:15]
.LBB0_836:
	s_and_b32 s40, s36, 3
	s_mulk_i32 s40, 0x4800
	v_add_u32_e32 v192, s40, v204
	ds_read_b128 v[120:123], v192
	ds_read_b128 v[124:127], v192 offset:32
	ds_read_b128 v[128:131], v192 offset:4608
	ds_read_b128 v[132:135], v192 offset:4640
	ds_read_b128 v[136:139], v192 offset:64
	ds_read_b128 v[140:143], v192 offset:96
	ds_read_b128 v[144:147], v192 offset:4672
	ds_read_b128 v[148:151], v192 offset:4704
	s_waitcnt lgkmcnt(0)
	s_barrier
	s_setprio 1
	s_and_b32 s10, s37, 3
	s_mulk_i32 s10, 0x4800
	v_add_u32_e32 v196, s10, v204
	v_mfma_f32_32x32x16_bf16 v[32:47], v[120:123], v[96:99], 0
	ds_read_b128 v[152:155], v196 offset:9216
	ds_read_b128 v[160:163], v196 offset:13824
	v_cvt_pk_bf16_f32 v176, v64, v65
	v_cvt_pk_bf16_f32 v177, v66, v67
	v_cvt_pk_bf16_f32 v178, v68, v69
	v_cvt_pk_bf16_f32 v179, v70, v71
	v_add_f32_e32 v174, v64, v174
	v_add_f32_e32 v175, v80, v175
	v_mfma_f32_32x32x16_bf16 v[48:63], v[128:131], v[96:99], 0
	ds_read_b128 v[156:159], v196 offset:9248
	ds_read_b128 v[164:167], v196 offset:13856
	v_cvt_pk_bf16_f32 v180, v72, v73
	v_cvt_pk_bf16_f32 v181, v74, v75
	v_cvt_pk_bf16_f32 v182, v76, v77
	v_cvt_pk_bf16_f32 v183, v78, v79
	v_add_f32_e32 v174, v65, v174
	v_add_f32_e32 v175, v81, v175
	v_mfma_f32_32x32x16_bf16 v[32:47], v[124:127], v[100:103], v[32:47]
	v_cvt_pk_bf16_f32 v184, v80, v81
	v_cvt_pk_bf16_f32 v185, v82, v83
	v_cvt_pk_bf16_f32 v186, v84, v85
	v_cvt_pk_bf16_f32 v187, v86, v87
	v_add_f32_e32 v174, v66, v174
	v_add_f32_e32 v175, v82, v175
	v_mfma_f32_32x32x16_bf16 v[48:63], v[132:135], v[100:103], v[48:63]
	v_cvt_pk_bf16_f32 v188, v88, v89
	v_cvt_pk_bf16_f32 v189, v90, v91
	v_cvt_pk_bf16_f32 v190, v92, v93
	v_cvt_pk_bf16_f32 v191, v94, v95
	v_add_f32_e32 v174, v67, v174
	v_add_f32_e32 v175, v83, v175
	v_mfma_f32_32x32x16_bf16 v[32:47], v[136:139], v[104:107], v[32:47]
	v_add_f32_e32 v174, v68, v174
	v_add_f32_e32 v175, v84, v175
	v_add_f32_e32 v174, v69, v174
	v_add_f32_e32 v175, v85, v175
	v_add_f32_e32 v174, v70, v174
	v_add_f32_e32 v175, v86, v175
	v_mfma_f32_32x32x16_bf16 v[48:63], v[144:147], v[104:107], v[48:63]
	v_add_f32_e32 v174, v71, v174
	v_add_f32_e32 v175, v87, v175
	v_add_f32_e32 v174, v72, v174
	v_add_f32_e32 v175, v88, v175
	v_add_f32_e32 v174, v73, v174
	v_add_f32_e32 v175, v89, v175
	v_mfma_f32_32x32x16_bf16 v[32:47], v[140:143], v[108:111], v[32:47]
	v_add_f32_e32 v174, v74, v174
	v_add_f32_e32 v175, v90, v175
	v_add_f32_e32 v174, v75, v174
	v_add_f32_e32 v175, v91, v175
	v_add_f32_e32 v174, v76, v174
	v_add_f32_e32 v175, v92, v175
	v_mfma_f32_32x32x16_bf16 v[48:63], v[148:151], v[108:111], v[48:63]
	v_add_f32_e32 v174, v77, v174
	v_add_f32_e32 v175, v93, v175
	v_add_f32_e32 v174, v78, v174
	v_add_f32_e32 v175, v94, v175
	v_add_f32_e32 v174, v79, v174
	v_add_f32_e32 v175, v95, v175
	ds_read_b128 v[120:123], v196 offset:9280
	ds_read_b128 v[124:127], v196 offset:13888
	ds_read_b128 v[128:131], v196 offset:9312
	ds_read_b128 v[132:135], v196 offset:13920
	s_andn2_b64 vcc, exec, s[38:39]
	s_cbranch_vccnz .LBB0_832
	s_nop 3
	v_sub_f32_e32 v47, v47, v200
	v_sub_f32_e32 v46, v46, v200
	v_sub_f32_e32 v45, v45, v200
	v_sub_f32_e32 v44, v44, v200
	v_sub_f32_e32 v43, v43, v200
	v_sub_f32_e32 v42, v42, v200
	v_sub_f32_e32 v41, v41, v200
	v_sub_f32_e32 v40, v40, v200
	v_sub_f32_e32 v39, v39, v200
	v_sub_f32_e32 v38, v38, v200
	v_sub_f32_e32 v37, v37, v200
	v_sub_f32_e32 v36, v36, v200
	v_sub_f32_e32 v35, v35, v200
	v_sub_f32_e32 v34, v34, v200
	v_sub_f32_e32 v33, v33, v200
	v_sub_f32_e32 v32, v32, v200
	v_sub_f32_e32 v63, v63, v200
	v_sub_f32_e32 v62, v62, v200
	v_sub_f32_e32 v61, v61, v200
	v_sub_f32_e32 v60, v60, v200
	v_sub_f32_e32 v59, v59, v200
	v_sub_f32_e32 v58, v58, v200
	v_sub_f32_e32 v57, v57, v200
	v_sub_f32_e32 v56, v56, v200
	v_sub_f32_e32 v55, v55, v200
	v_sub_f32_e32 v54, v54, v200
	v_sub_f32_e32 v53, v53, v200
	v_sub_f32_e32 v52, v52, v200
	v_sub_f32_e32 v51, v51, v200
	v_sub_f32_e32 v50, v50, v200
	v_sub_f32_e32 v49, v49, v200
	v_sub_f32_e32 v48, v48, v200
.LBB0_832:
	s_waitcnt lgkmcnt(7)
	v_mfma_f32_32x32x16_bf16 v[0:15], v[152:155], v[176:179], v[0:15]
	v_exp_f32_e32 v64, v32
	v_exp_f32_e32 v65, v33
	v_exp_f32_e32 v66, v34
	v_exp_f32_e32 v67, v35
	s_waitcnt lgkmcnt(6)
	v_mfma_f32_32x32x16_bf16 v[16:31], v[160:163], v[176:179], v[16:31]
	v_exp_f32_e32 v68, v36
	v_exp_f32_e32 v69, v37
	v_exp_f32_e32 v70, v38
	v_exp_f32_e32 v71, v39
	s_waitcnt lgkmcnt(5)
	v_mfma_f32_32x32x16_bf16 v[0:15], v[156:159], v[180:183], v[0:15]
	v_exp_f32_e32 v72, v40
	v_exp_f32_e32 v73, v41
	v_exp_f32_e32 v74, v42
	v_exp_f32_e32 v75, v43
	s_waitcnt lgkmcnt(4)
	v_mfma_f32_32x32x16_bf16 v[16:31], v[164:167], v[180:183], v[16:31]
	v_exp_f32_e32 v76, v44
	v_exp_f32_e32 v77, v45
	v_exp_f32_e32 v78, v46
	v_exp_f32_e32 v79, v47
	s_waitcnt lgkmcnt(3)
	v_mfma_f32_32x32x16_bf16 v[0:15], v[120:123], v[184:187], v[0:15]
	v_exp_f32_e32 v80, v48
	v_exp_f32_e32 v81, v49
	v_exp_f32_e32 v82, v50
	v_exp_f32_e32 v83, v51
	s_waitcnt lgkmcnt(2)
	v_mfma_f32_32x32x16_bf16 v[16:31], v[124:127], v[184:187], v[16:31]
	v_exp_f32_e32 v84, v52
	v_exp_f32_e32 v85, v53
	v_exp_f32_e32 v86, v54
	v_exp_f32_e32 v87, v55
	s_waitcnt lgkmcnt(1)
	v_mfma_f32_32x32x16_bf16 v[0:15], v[128:131], v[188:191], v[0:15]
	v_exp_f32_e32 v88, v56
	v_exp_f32_e32 v89, v57
	v_exp_f32_e32 v90, v58
	v_exp_f32_e32 v91, v59
	s_waitcnt lgkmcnt(0)
	v_mfma_f32_32x32x16_bf16 v[16:31], v[132:135], v[188:191], v[16:31]
	v_exp_f32_e32 v92, v60
	v_exp_f32_e32 v93, v61
	v_exp_f32_e32 v94, v62
	v_exp_f32_e32 v95, v63
	s_setprio 0
	s_barrier
	s_cmpk_eq_i32 s36, 0x100
	s_mov_b32 s37, s36
	s_cbranch_scc0 .LBB0_830

;     ...
;   const int wid = tid >> 6, lane = tid & 63, wr = wid >> 1, wc = wid & 1, fr = lane & 15, fq = lane >> 4;
;   acc_t acc;
; #pragma unroll
;   for (int m = 0; m < 4; ++m)
; #pragma unroll
;     for (int n = 0; n < 4; ++n) acc[m][n] = f32x4{0.f, 0.f, 0.f, 0.f};
;   const int nt = K / BK;
;   unsigned oA0, oA1, oB0, oB1;
;   { int _r, _c; stage_rc(tid * 16, _r, _c); oA0 = _r * lda + _c; oB0 = _r * ldb + _c;
;     stage_rc(tid * 16 + 8192, _r, _c); oA1 = _r * lda + _c; oB1 = _r * ldb + _c; }
;     ...
;       __builtin_amdgcn_s_setprio(1);
; #pragma unroll
;       for (int k = 0; k < 2; ++k)
; #pragma unroll
;         for (int m = 0; m < 4; ++m)
; #pragma unroll
;           for (int n = 0; n < 4; ++n) acc[m][n] = __builtin_amdgcn_mfma_f32_16x16x32_bf16(Bf[n][k], At[m][k], acc[m][n], 0, 0, 0);
.LBB0_1020:
	s_or_b64 exec, exec, s[10:11]
	v_lshlrev_b32_e32 v4, 13, v4
	s_ashr_i32 s41, s40, 31
	s_ashr_i32 s39, s38, 31
	v_and_b32_e32 v4, 0xffffc000, v4
	v_lshlrev_b32_e32 v0, 13, v0
	v_and_b32_e32 v8, 15, v133
	v_and_b32_e32 v9, 48, v133
	s_lshl_b64 s[10:11], s[40:41], 11
	s_lshl_b64 s[36:37], s[38:39], 11
	v_lshl_add_u32 v4, v5, 10, v4
	v_and_b32_e32 v0, 0xffffc000, v0
	v_lshl_or_b32 v8, v8, 6, v9
	v_lshlrev_b32_e32 v9, 2, v133
	v_or_b32_e32 v4, v4, v6
	s_add_u32 s36, s50, s36
	v_lshl_add_u32 v0, v1, 10, v0
	v_and_b32_e32 v9, 32, v9
	v_add_u32_sdwa v196, v4, sext(v7) dst_sel:DWORD dst_unused:UNUSED_PAD src0_sel:DWORD src1_sel:WORD_0
	s_addc_u32 s37, s51, s37
	v_or_b32_e32 v0, v0, v2
	v_xad_u32 v8, v8, v9, 16
	v_lshlrev_b32_e32 v9, 6, v133
	v_lshlrev_b32_e32 v10, 7, v133
	v_lshlrev_b64 v[4:5], 1, v[196:197]
	v_add_u32_sdwa v196, v0, sext(v3) dst_sel:DWORD dst_unused:UNUSED_PAD src0_sel:DWORD src1_sel:WORD_0
	s_add_u32 s10, s54, s10
	v_and_b32_e32 v9, 0x2000, v9
	v_and_b32_e32 v10, 0x2000, v10
	v_lshlrev_b64 v[0:1], 1, v[196:197]
	s_addc_u32 s11, s55, s11
	v_mov_b32_e32 v56, 0
	v_ashrrev_i32_e32 v132, 8, v133
	v_add_u32_e32 v129, v8, v9
	v_add_u32_e32 v131, v8, v10
	v_lshl_add_u64 v[134:135], s[36:37], 0, v[4:5]
	v_lshl_add_u64 v[136:137], s[36:37], 0, v[0:1]
	v_lshl_add_u64 v[138:139], s[10:11], 0, v[4:5]
	v_lshl_add_u64 v[140:141], s[10:11], 0, v[0:1]
	s_mov_b32 s39, 0
	s_mov_b64 s[10:11], 0
	s_mov_b32 s41, 0
	v_mov_b32_e32 v57, v56
	v_mov_b32_e32 v58, v56
	v_mov_b32_e32 v59, v56
	v_mov_b32_e32 v60, v56
	v_mov_b32_e32 v61, v56
	v_mov_b32_e32 v62, v56
	v_mov_b32_e32 v63, v56
	v_mov_b32_e32 v52, v56
	v_mov_b32_e32 v53, v56
	v_mov_b32_e32 v54, v56
	v_mov_b32_e32 v55, v56
	v_mov_b32_e32 v48, v56
	v_mov_b32_e32 v49, v56
	v_mov_b32_e32 v50, v56
	v_mov_b32_e32 v51, v56
	v_mov_b32_e32 v44, v56
	v_mov_b32_e32 v45, v56
	v_mov_b32_e32 v46, v56
	v_mov_b32_e32 v47, v56
	v_mov_b32_e32 v40, v56
	v_mov_b32_e32 v41, v56
	v_mov_b32_e32 v42, v56
	v_mov_b32_e32 v43, v56
	v_mov_b32_e32 v36, v56
	v_mov_b32_e32 v37, v56
	v_mov_b32_e32 v38, v56
	v_mov_b32_e32 v39, v56
	v_mov_b32_e32 v32, v56
	v_mov_b32_e32 v33, v56
	v_mov_b32_e32 v34, v56
	v_mov_b32_e32 v35, v56
	v_mov_b32_e32 v28, v56
	v_mov_b32_e32 v29, v56
	v_mov_b32_e32 v30, v56
	v_mov_b32_e32 v31, v56
	v_mov_b32_e32 v24, v56
	v_mov_b32_e32 v25, v56
	v_mov_b32_e32 v26, v56
	v_mov_b32_e32 v27, v56
	v_mov_b32_e32 v20, v56
	v_mov_b32_e32 v21, v56
	v_mov_b32_e32 v22, v56
	v_mov_b32_e32 v23, v56
	v_mov_b32_e32 v16, v56
	v_mov_b32_e32 v17, v56
	v_mov_b32_e32 v18, v56
	v_mov_b32_e32 v19, v56
	v_mov_b32_e32 v12, v56
	v_mov_b32_e32 v13, v56
	v_mov_b32_e32 v14, v56
	v_mov_b32_e32 v15, v56
	v_mov_b32_e32 v8, v56
	v_mov_b32_e32 v9, v56
	v_mov_b32_e32 v10, v56
	v_mov_b32_e32 v11, v56
	v_mov_b32_e32 v4, v56
	v_mov_b32_e32 v5, v56
	v_mov_b32_e32 v6, v56
	v_mov_b32_e32 v7, v56
	v_mov_b32_e32 v0, v56
	v_mov_b32_e32 v1, v56
	v_mov_b32_e32 v2, v56
	v_mov_b32_e32 v3, v56
	v_readfirstlane_b32 s99, v151
	v_lshl_add_u32 v174, v132, 14, v129
	v_mov_b32_e32 v161, v131
	v_lshl_add_u64 v[162:163], v[140:141], 0, s[20:21]
	v_lshl_add_u64 v[164:165], v[138:139], 0, s[20:21]
	v_lshl_add_u64 v[166:167], v[140:141], 0, s[22:23]
	v_lshl_add_u64 v[168:169], v[138:139], 0, s[22:23]
	v_mov_b64_e32 v[170:171], v[136:137]
	v_mov_b64_e32 v[172:173], v[134:135]
	v_mov_b32_e32 v160, v174
	s_add_u32 s98, s99, 0x18000
	s_branch .LBB0_1022
.LBB0_1021:
	s_waitcnt lgkmcnt(0)
	s_barrier
	s_setprio 1
	s_waitcnt lgkmcnt(0)
	v_mfma_f32_16x16x32_bf16 v[56:59], v[112:115], v[108:111], v[56:59]
	v_mfma_f32_16x16x32_bf16 v[60:63], v[116:119], v[108:111], v[60:63]
	v_mfma_f32_16x16x32_bf16 v[52:55], v[120:123], v[108:111], v[52:55]
	v_mfma_f32_16x16x32_bf16 v[48:51], v[124:127], v[108:111], v[48:51]
	v_mfma_f32_16x16x32_bf16 v[44:47], v[112:115], v[104:107], v[44:47]
	v_mfma_f32_16x16x32_bf16 v[40:43], v[116:119], v[104:107], v[40:43]
	v_mfma_f32_16x16x32_bf16 v[36:39], v[120:123], v[104:107], v[36:39]
	v_mfma_f32_16x16x32_bf16 v[32:35], v[124:127], v[104:107], v[32:35]
	s_cmp_gt_u32 s41, 13
	s_cbranch_scc1 .Lgc4_skd3
	s_add_u32 m0, s98, 0x6000
	s_nop 0
	global_load_lds_dwordx4 v[168:169], off

;     ...
;       __builtin_amdgcn_s_setprio(1);
; #pragma unroll
;       for (int k = 0; k < 2; ++k)
; #pragma unroll
;         for (int m = 0; m < 4; ++m)
; #pragma unroll
;           for (int n = 0; n < 4; ++n) acc[m][n] = __builtin_amdgcn_mfma_f32_16x16x32_bf16(Bf[n][k], At[m][k], acc[m][n], 0, 0, 0);
.Lgc4_skd4:
	v_mfma_f32_16x16x32_bf16 v[56:59], v[80:83], v[76:79], v[56:59]
	v_mfma_f32_16x16x32_bf16 v[60:63], v[84:87], v[76:79], v[60:63]
	v_mfma_f32_16x16x32_bf16 v[52:55], v[88:91], v[76:79], v[52:55]
	v_mfma_f32_16x16x32_bf16 v[48:51], v[92:95], v[76:79], v[48:51]
	v_mfma_f32_16x16x32_bf16 v[44:47], v[80:83], v[72:75], v[44:47]
	v_mfma_f32_16x16x32_bf16 v[40:43], v[84:87], v[72:75], v[40:43]
	v_mfma_f32_16x16x32_bf16 v[36:39], v[88:91], v[72:75], v[36:39]
	v_mfma_f32_16x16x32_bf16 v[32:35], v[92:95], v[72:75], v[32:35]
	s_cmp_gt_u32 s41, 13
	s_cbranch_scc1 .Lgc4_skd5
	s_add_u32 m0, s98, 0xa000
	s_nop 0
	global_load_lds_dwordx4 v[172:173], off

; #define STAGE_ALL(bufi, kt) do { STAGEA(SA(bufi, 0), brow, kt); STAGEA(SA(bufi, 1), brow + HALF, kt); STAGEB(SB(bufi), bcol, kt); } while (0)
; #define WAIT_V(n) asm volatile("s_waitcnt vmcnt(" #n ")" ::: "memory")
; #define BAR __builtin_amdgcn_s_barrier()
;     ...
;   const int wid = tid >> 6, lane = tid & 63, wr = wid >> 1, wc = wid & 1, fr = lane & 15, fq = lane >> 4;
;   acc_t acc;
; #pragma unroll
;   for (int m = 0; m < 4; ++m)
; #pragma unroll
;     for (int n = 0; n < 4; ++n) acc[m][n] = f32x4{0.f, 0.f, 0.f, 0.f};
;   const int nt = K / BK;
;   unsigned oA0, oA1, oB0, oB1;
;   { int _r, _c; stage_rc(tid * 16, _r, _c); oA0 = _r * lda + _c; oB0 = _r * ldb + _c;
;     stage_rc(tid * 16 + 8192, _r, _c); oA1 = _r * lda + _c; oB1 = _r * ldb + _c; }
;     ...
;     for (int t = 0; t < nt; ++t) {
;       const char* pa = (const char*)SA(b, wr >> 1);
;       const char* pb = (const char*)SB(b);
;       bf16x8 At[4][2], Bf[4][2];
; #pragma unroll
;       for (int m = 0; m < 4; ++m)
; #pragma unroll
;         for (int k = 0; k < 2; ++k) At[m][k] = *reinterpret_cast<const bf16x8*>(pa + lds_byte((wr & 1) * 64 + m * 16 + fr, k * 32 + fq * 8));
; #pragma unroll
;       for (int n = 0; n < 4; ++n)
; #pragma unroll
;         for (int k = 0; k < 2; ++k) Bf[n][k] = *reinterpret_cast<const bf16x8*>(pb + lds_byte(wc * 64 + n * 16 + fr, k * 32 + fq * 8));
;       if (t + 2 < nt) { const int b2 = (b == 0) ? 2 : b - 1; STAGE_ALL(b2, t + 2); WAIT_V(6); } else { WAIT_V(0); }
;       asm volatile("s_waitcnt lgkmcnt(0)" ::: "memory");
;       __builtin_amdgcn_sched_barrier(0);
;       BAR;
;       __builtin_amdgcn_sched_barrier(0);
;       __builtin_amdgcn_s_setprio(1);
; #pragma unroll
;       for (int k = 0; k < 2; ++k)
; #pragma unroll
;         for (int m = 0; m < 4; ++m)
; #pragma unroll
;           for (int n = 0; n < 4; ++n) acc[m][n] = __builtin_amdgcn_mfma_f32_16x16x32_bf16(Bf[n][k], At[m][k], acc[m][n], 0, 0, 0);
.LBB0_1056:
	s_or_b64 exec, exec, s[10:11]
	v_and_b32_e32 v8, 15, v133
	v_and_b32_e32 v9, 48, v133
	v_lshl_or_b32 v8, v8, 6, v9
	v_lshlrev_b32_e32 v9, 2, v133
	v_and_b32_e32 v9, 32, v9
	v_xad_u32 v8, v8, v9, 16
	v_lshlrev_b32_e32 v9, 6, v133
	v_lshlrev_b32_e32 v10, 7, v133
	v_and_b32_e32 v9, 0x2000, v9
	v_and_b32_e32 v10, 0x2000, v10
	s_movk_i32 s60, 0xb00
	v_add_u32_e32 v129, v8, v9
	v_add_u32_e32 v131, v8, v10
	v_lshrrev_b32_e32 v8, 1, v4
	v_mul_lo_u32 v4, v6, s60
	s_mov_b32 s61, 0xb000
	v_mad_u64_u32 v[8:9], s[10:11], v8, s61, v[4:5]
	v_or_b32_e32 v4, v8, v5
	s_add_u32 s10, s46, s41
	v_lshrrev_b32_e32 v6, 1, v0
	v_mul_lo_u32 v0, v2, s60
	v_add_u32_sdwa v196, v4, sext(v7) dst_sel:DWORD dst_unused:UNUSED_PAD src0_sel:DWORD src1_sel:WORD_0
	s_addc_u32 s11, s47, s40
	v_mad_u64_u32 v[6:7], s[40:41], v6, s61, v[0:1]
	v_or_b32_e32 v0, v6, v1
	v_lshlrev_b64 v[4:5], 1, v[196:197]
	v_add_u32_sdwa v196, v0, sext(v3) dst_sel:DWORD dst_unused:UNUSED_PAD src0_sel:DWORD src1_sel:WORD_0
	v_lshlrev_b64 v[0:1], 1, v[196:197]
	v_lshl_add_u64 v[134:135], s[10:11], 0, v[4:5]
	v_lshl_add_u64 v[136:137], s[10:11], 0, v[0:1]
	s_add_u32 s10, s54, s37
	s_addc_u32 s11, s55, s36
	v_mov_b32_e32 v60, 0
	v_ashrrev_i32_e32 v132, 8, v133
	v_lshl_add_u64 v[138:139], s[10:11], 0, v[4:5]
	v_lshl_add_u64 v[140:141], s[10:11], 0, v[0:1]
	s_mov_b32 s60, 0
	s_mov_b64 s[10:11], 0
	s_mov_b32 s61, 0
	v_mov_b32_e32 v61, v60
	v_mov_b32_e32 v62, v60
	v_mov_b32_e32 v63, v60
	v_mov_b32_e32 v56, v60
	v_mov_b32_e32 v57, v60
	v_mov_b32_e32 v58, v60
	v_mov_b32_e32 v59, v60
	v_mov_b32_e32 v52, v60
	v_mov_b32_e32 v53, v60
	v_mov_b32_e32 v54, v60
	v_mov_b32_e32 v55, v60
	v_mov_b32_e32 v48, v60
	v_mov_b32_e32 v49, v60
	v_mov_b32_e32 v50, v60
	v_mov_b32_e32 v51, v60
	v_mov_b32_e32 v44, v60
	v_mov_b32_e32 v45, v60
	v_mov_b32_e32 v46, v60
	v_mov_b32_e32 v47, v60
	v_mov_b32_e32 v40, v60
	v_mov_b32_e32 v41, v60
	v_mov_b32_e32 v42, v60
	v_mov_b32_e32 v43, v60
	v_mov_b32_e32 v36, v60
	v_mov_b32_e32 v37, v60
	v_mov_b32_e32 v38, v60
	v_mov_b32_e32 v39, v60
	v_mov_b32_e32 v32, v60
	v_mov_b32_e32 v33, v60
	v_mov_b32_e32 v34, v60
	v_mov_b32_e32 v35, v60
	v_mov_b32_e32 v28, v60
	v_mov_b32_e32 v29, v60
	v_mov_b32_e32 v30, v60
	v_mov_b32_e32 v31, v60
	v_mov_b32_e32 v24, v60
	v_mov_b32_e32 v25, v60
	v_mov_b32_e32 v26, v60
	v_mov_b32_e32 v27, v60
	v_mov_b32_e32 v20, v60
	v_mov_b32_e32 v21, v60
	v_mov_b32_e32 v22, v60
	v_mov_b32_e32 v23, v60
	v_mov_b32_e32 v16, v60
	v_mov_b32_e32 v17, v60
	v_mov_b32_e32 v18, v60
	v_mov_b32_e32 v19, v60
	v_mov_b32_e32 v12, v60
	v_mov_b32_e32 v13, v60
	v_mov_b32_e32 v14, v60
	v_mov_b32_e32 v15, v60
	v_mov_b32_e32 v8, v60
	v_mov_b32_e32 v9, v60
	v_mov_b32_e32 v10, v60
	v_mov_b32_e32 v11, v60
	v_mov_b32_e32 v4, v60
	v_mov_b32_e32 v5, v60
	v_mov_b32_e32 v6, v60
	v_mov_b32_e32 v7, v60
	v_mov_b32_e32 v0, v60
	v_mov_b32_e32 v1, v60
	v_mov_b32_e32 v2, v60
	v_mov_b32_e32 v3, v60
	v_readfirstlane_b32 s99, v151
	v_lshl_add_u32 v174, v132, 14, v129
	v_mov_b32_e32 v161, v131
	v_lshl_add_u64 v[162:163], v[140:141], 0, s[16:17]
	v_lshl_add_u64 v[164:165], v[138:139], 0, s[16:17]
	v_lshl_add_u64 v[166:167], v[140:141], 0, s[18:19]
	v_lshl_add_u64 v[168:169], v[138:139], 0, s[18:19]
	v_mov_b64_e32 v[170:171], v[136:137]
	v_mov_b64_e32 v[172:173], v[134:135]
	v_mov_b32_e32 v160, v174
	s_add_u32 s98, s99, 0x18000
	s_branch .LBB0_1058
.LBB0_1057:
	s_waitcnt lgkmcnt(0)
	s_barrier
	s_setprio 1
	s_waitcnt lgkmcnt(0)
	v_mfma_f32_16x16x32_bf16 v[60:63], v[112:115], v[108:111], v[60:63]
	v_mfma_f32_16x16x32_bf16 v[56:59], v[116:119], v[108:111], v[56:59]
	v_mfma_f32_16x16x32_bf16 v[52:55], v[120:123], v[108:111], v[52:55]
	v_mfma_f32_16x16x32_bf16 v[48:51], v[124:127], v[108:111], v[48:51]
	v_mfma_f32_16x16x32_bf16 v[44:47], v[112:115], v[104:107], v[44:47]
	v_mfma_f32_16x16x32_bf16 v[40:43], v[116:119], v[104:107], v[40:43]
	v_mfma_f32_16x16x32_bf16 v[36:39], v[120:123], v[104:107], v[36:39]
	v_mfma_f32_16x16x32_bf16 v[32:35], v[124:127], v[104:107], v[32:35]
	s_cmp_gt_u32 s61, 41
	s_cbranch_scc1 .Lgc5_skd3
	s_add_u32 m0, s98, 0x6000
	s_nop 0
	global_load_lds_dwordx4 v[168:169], off
; #define STAGE_ALL(bufi, kt) do { STAGEA(SA(bufi, 0), brow, kt); STAGEA(SA(bufi, 1), brow + HALF, kt); STAGEB(SB(bufi), bcol, kt); } while (0)
; #define WAIT_V(n) asm volatile("s_waitcnt vmcnt(" #n ")" ::: "memory")
; #define BAR __builtin_amdgcn_s_barrier()
;     ...
;     for (int t = 0; t < nt; ++t) {
;       const char* pa = (const char*)SA(b, wr >> 1);
;       const char* pb = (const char*)SB(b);
;       bf16x8 At[4][2], Bf[4][2];
; #pragma unroll
;       for (int m = 0; m < 4; ++m)
; #pragma unroll
;         for (int k = 0; k < 2; ++k) At[m][k] = *reinterpret_cast<const bf16x8*>(pa + lds_byte((wr & 1) * 64 + m * 16 + fr, k * 32 + fq * 8));
; #pragma unroll
;       for (int n = 0; n < 4; ++n)
; #pragma unroll
;         for (int k = 0; k < 2; ++k) Bf[n][k] = *reinterpret_cast<const bf16x8*>(pb + lds_byte(wc * 64 + n * 16 + fr, k * 32 + fq * 8));
;       if (t + 2 < nt) { const int b2 = (b == 0) ? 2 : b - 1; STAGE_ALL(b2, t + 2); WAIT_V(6); } else { WAIT_V(0); }
;       asm volatile("s_waitcnt lgkmcnt(0)" ::: "memory");
;       __builtin_amdgcn_sched_barrier(0);
;       BAR;
;       __builtin_amdgcn_sched_barrier(0);
;       __builtin_amdgcn_s_setprio(1);
; #pragma unroll
;       for (int k = 0; k < 2; ++k)
; #pragma unroll
;         for (int m = 0; m < 4; ++m)
; #pragma unroll
;           for (int n = 0; n < 4; ++n) acc[m][n] = __builtin_amdgcn_mfma_f32_16x16x32_bf16(Bf[n][k], At[m][k], acc[m][n], 0, 0, 0);
;       __builtin_amdgcn_s_setprio(0);
;       __builtin_amdgcn_sched_barrier(0);
;       BAR;
;       __builtin_amdgcn_sched_barrier(0);
;       b = (b == 2) ? 0 : b + 1;
;     }
.Lgc5_skd3:
	v_mfma_f32_16x16x32_bf16 v[28:31], v[112:115], v[100:103], v[28:31]
	v_mfma_f32_16x16x32_bf16 v[24:27], v[116:119], v[100:103], v[24:27]
	v_mfma_f32_16x16x32_bf16 v[20:23], v[120:123], v[100:103], v[20:23]
	v_mfma_f32_16x16x32_bf16 v[16:19], v[124:127], v[100:103], v[16:19]
	v_mfma_f32_16x16x32_bf16 v[12:15], v[112:115], v[96:99], v[12:15]
	v_mfma_f32_16x16x32_bf16 v[8:11], v[116:119], v[96:99], v[8:11]
	v_mfma_f32_16x16x32_bf16 v[4:7], v[120:123], v[96:99], v[4:7]
	v_mfma_f32_16x16x32_bf16 v[0:3], v[124:127], v[96:99], v[0:3]
	s_cmp_gt_u32 s61, 41
	s_cbranch_scc1 .Lgc5_skd4
	s_add_u32 m0, s98, 0x8000
	s_nop 0
	global_load_lds_dwordx4 v[170:171], off
.Lgc5_skd4:
	v_mfma_f32_16x16x32_bf16 v[60:63], v[80:83], v[76:79], v[60:63]
	v_mfma_f32_16x16x32_bf16 v[56:59], v[84:87], v[76:79], v[56:59]
	v_mfma_f32_16x16x32_bf16 v[52:55], v[88:91], v[76:79], v[52:55]
	v_mfma_f32_16x16x32_bf16 v[48:51], v[92:95], v[76:79], v[48:51]
	v_mfma_f32_16x16x32_bf16 v[44:47], v[80:83], v[72:75], v[44:47]
	v_mfma_f32_16x16x32_bf16 v[40:43], v[84:87], v[72:75], v[40:43]
	v_mfma_f32_16x16x32_bf16 v[36:39], v[88:91], v[72:75], v[36:39]
	v_mfma_f32_16x16x32_bf16 v[32:35], v[92:95], v[72:75], v[32:35]
	s_cmp_gt_u32 s61, 41
	s_cbranch_scc1 .Lgc5_skd5
	s_add_u32 m0, s98, 0xa000
	s_nop 0
	global_load_lds_dwordx4 v[172:173], off
.Lgc5_skd5:
	v_mfma_f32_16x16x32_bf16 v[28:31], v[80:83], v[68:71], v[28:31]
	v_mfma_f32_16x16x32_bf16 v[24:27], v[84:87], v[68:71], v[24:27]
	v_mfma_f32_16x16x32_bf16 v[20:23], v[88:91], v[68:71], v[20:23]
	v_mfma_f32_16x16x32_bf16 v[16:19], v[92:95], v[68:71], v[16:19]
	v_mfma_f32_16x16x32_bf16 v[12:15], v[80:83], v[64:67], v[12:15]
	v_mfma_f32_16x16x32_bf16 v[8:11], v[84:87], v[64:67], v[8:11]
	v_mfma_f32_16x16x32_bf16 v[4:7], v[88:91], v[64:67], v[4:7]
	v_mfma_f32_16x16x32_bf16 v[0:3], v[92:95], v[64:67], v[0:3]
	s_setprio 0
	s_add_i32 s36, s60, 1
	s_cmp_lg_u32 s60, 2
	s_cselect_b32 s60, s36, 0
	s_add_i32 s61, s61, 1
	s_add_u32 s10, s10, 0x80
	s_addc_u32 s11, s11, 0
	s_mul_i32 s36, s60, 0xc000
	v_add_u32_e32 v160, s36, v174
	v_add_u32_e32 v161, s36, v131
	s_mul_i32 s36, s60, 0x6000
	s_addk_i32 s36, 0xa000
	s_cmp_lg_u32 s60, 0
	s_cselect_b32 s36, s36, 0xc000
	s_lshl_b32 s36, s36, 1
	s_add_u32 s98, s36, s99
	v_lshl_add_u64 v[162:163], v[162:163], 0, s[14:15]
	v_lshl_add_u64 v[164:165], v[164:165], 0, s[14:15]
	v_lshl_add_u64 v[166:167], v[166:167], 0, s[14:15]
	v_lshl_add_u64 v[168:169], v[168:169], 0, s[14:15]
	v_lshl_add_u64 v[170:171], v[170:171], 0, s[14:15]
	v_lshl_add_u64 v[172:173], v[172:173], 0, s[14:15]
	s_barrier
	s_cmpk_eq_i32 s10, 0x1600
	s_cbranch_scc1 .LBB0_1062
.LBB0_1058:
	ds_read_b128 v[108:111], v160
	ds_read_b128 v[76:79], v160 offset:1024
	ds_read_b128 v[104:107], v160 offset:2048
	ds_read_b128 v[72:75], v160 offset:3072
	ds_read_b128 v[100:103], v160 offset:4096
	ds_read_b128 v[68:71], v160 offset:5120
	ds_read_b128 v[96:99], v160 offset:6144
	ds_read_b128 v[64:67], v160 offset:7168
	ds_read_b128 v[112:115], v161 offset:32768
	ds_read_b128 v[80:83], v161 offset:33792
	ds_read_b128 v[116:119], v161 offset:34816
	ds_read_b128 v[84:87], v161 offset:35840
	ds_read_b128 v[120:123], v161 offset:36864
	ds_read_b128 v[88:91], v161 offset:37888
	ds_read_b128 v[124:127], v161 offset:38912
	ds_read_b128 v[92:95], v161 offset:39936
	s_cmp_gt_u32 s61, 41
	s_cbranch_scc1 .Lgc5_nostage
	s_mov_b32 m0, s98
	s_nop 0
	global_load_lds_dwordx4 v[162:163], off
	s_add_u32 m0, s98, 0x2000
	s_nop 0
	global_load_lds_dwordx4 v[164:165], off
	s_add_u32 m0, s98, 0x4000
	s_nop 0
	global_load_lds_dwordx4 v[166:167], off
	s_waitcnt vmcnt(3)
	s_branch .LBB0_1057

; #define STAGE_ALL(bufi, kt) do { STAGEA(SA(bufi, 0), brow, kt); STAGEA(SA(bufi, 1), brow + HALF, kt); STAGEB(SB(bufi), bcol, kt); } while (0)
; #define WAIT_V(n) asm volatile("s_waitcnt vmcnt(" #n ")" ::: "memory")
; #define BAR __builtin_amdgcn_s_barrier()
;     ...
;   const int wid = tid >> 6, lane = tid & 63, wr = wid >> 1, wc = wid & 1, fr = lane & 15, fq = lane >> 4;
;   acc_t acc;
; #pragma unroll
;   for (int m = 0; m < 4; ++m)
; #pragma unroll
;     for (int n = 0; n < 4; ++n) acc[m][n] = f32x4{0.f, 0.f, 0.f, 0.f};
;   const int nt = K / BK;
;   unsigned oA0, oA1, oB0, oB1;
;   { int _r, _c; stage_rc(tid * 16, _r, _c); oA0 = _r * lda + _c; oB0 = _r * ldb + _c;
;     stage_rc(tid * 16 + 8192, _r, _c); oA1 = _r * lda + _c; oB1 = _r * ldb + _c; }
;     ...
;     for (int t = 0; t < nt; ++t) {
;       const char* pa = (const char*)SA(b, wr >> 1);
;       const char* pb = (const char*)SB(b);
;       bf16x8 At[4][2], Bf[4][2];
; #pragma unroll
;       for (int m = 0; m < 4; ++m)
; #pragma unroll
;         for (int k = 0; k < 2; ++k) At[m][k] = *reinterpret_cast<const bf16x8*>(pa + lds_byte((wr & 1) * 64 + m * 16 + fr, k * 32 + fq * 8));
; #pragma unroll
;       for (int n = 0; n < 4; ++n)
; #pragma unroll
;         for (int k = 0; k < 2; ++k) Bf[n][k] = *reinterpret_cast<const bf16x8*>(pb + lds_byte(wc * 64 + n * 16 + fr, k * 32 + fq * 8));
;       if (t + 2 < nt) { const int b2 = (b == 0) ? 2 : b - 1; STAGE_ALL(b2, t + 2); WAIT_V(6); } else { WAIT_V(0); }
;       asm volatile("s_waitcnt lgkmcnt(0)" ::: "memory");
;       __builtin_amdgcn_sched_barrier(0);
;       BAR;
;       __builtin_amdgcn_sched_barrier(0);
;       __builtin_amdgcn_s_setprio(1);
; #pragma unroll
;       for (int k = 0; k < 2; ++k)
; #pragma unroll
;         for (int m = 0; m < 4; ++m)
; #pragma unroll
;           for (int n = 0; n < 4; ++n) acc[m][n] = __builtin_amdgcn_mfma_f32_16x16x32_bf16(Bf[n][k], At[m][k], acc[m][n], 0, 0, 0);
.LBB0_1264:
	s_or_b64 exec, exec, s[44:45]
	v_lshlrev_b32_e32 v4, 13, v4
	v_and_b32_e32 v4, 0xffffc000, v4
	v_lshlrev_b32_e32 v0, 13, v0
	v_lshl_add_u32 v4, v5, 10, v4
	v_and_b32_e32 v0, 0xffffc000, v0
	s_ashr_i32 s43, s42, 31
	s_ashr_i32 s11, s10, 31
	v_or_b32_e32 v4, v4, v6
	v_lshl_add_u32 v0, v1, 10, v0
	v_and_b32_e32 v8, 15, v141
	v_and_b32_e32 v9, 48, v141
	s_lshl_b64 s[36:37], s[42:43], 11
	s_lshl_b64 s[10:11], s[10:11], 11
	v_add_u32_sdwa v196, v4, sext(v7) dst_sel:DWORD dst_unused:UNUSED_PAD src0_sel:DWORD src1_sel:WORD_0
	v_or_b32_e32 v0, v0, v2
	v_lshl_or_b32 v8, v8, 6, v9
	v_lshlrev_b32_e32 v9, 2, v141
	v_lshlrev_b64 v[4:5], 1, v[196:197]
	s_add_u32 s10, s48, s10
	v_add_u32_sdwa v196, v0, sext(v3) dst_sel:DWORD dst_unused:UNUSED_PAD src0_sel:DWORD src1_sel:WORD_0
	v_and_b32_e32 v9, 32, v9
	s_addc_u32 s11, s49, s11
	v_lshlrev_b64 v[0:1], 1, v[196:197]
	v_xad_u32 v8, v8, v9, 16
	v_lshlrev_b32_e32 v9, 6, v141
	v_lshlrev_b32_e32 v10, 7, v141
	v_lshl_add_u64 v[132:133], s[10:11], 0, v[4:5]
	v_lshl_add_u64 v[134:135], s[10:11], 0, v[0:1]
	s_add_u32 s10, s54, s36
	v_and_b32_e32 v9, 0x2000, v9
	v_and_b32_e32 v10, 0x2000, v10
	s_addc_u32 s11, s55, s37
	v_mov_b32_e32 v56, 0
	v_add_u32_e32 v129, v8, v9
	v_add_u32_e32 v131, v8, v10
	v_lshl_add_u64 v[136:137], s[10:11], 0, v[4:5]
	v_lshl_add_u64 v[138:139], s[10:11], 0, v[0:1]
	s_mov_b32 s43, 0
	s_mov_b64 s[10:11], 0
	s_mov_b32 s58, 0
	v_mov_b32_e32 v57, v56
	v_mov_b32_e32 v58, v56
	v_mov_b32_e32 v59, v56
	v_mov_b32_e32 v48, v56
	v_mov_b32_e32 v49, v56
	v_mov_b32_e32 v50, v56
	v_mov_b32_e32 v51, v56
	v_mov_b32_e32 v60, v56
	v_mov_b32_e32 v61, v56
	v_mov_b32_e32 v62, v56
	v_mov_b32_e32 v63, v56
	v_mov_b32_e32 v52, v56
	v_mov_b32_e32 v53, v56
	v_mov_b32_e32 v54, v56
	v_mov_b32_e32 v55, v56
	v_mov_b32_e32 v40, v56
	v_mov_b32_e32 v41, v56
	v_mov_b32_e32 v42, v56
	v_mov_b32_e32 v43, v56
	v_mov_b32_e32 v32, v56
	v_mov_b32_e32 v33, v56
	v_mov_b32_e32 v34, v56
	v_mov_b32_e32 v35, v56
	v_mov_b32_e32 v44, v56
	v_mov_b32_e32 v45, v56
	v_mov_b32_e32 v46, v56
	v_mov_b32_e32 v47, v56
	v_mov_b32_e32 v36, v56
	v_mov_b32_e32 v37, v56
	v_mov_b32_e32 v38, v56
	v_mov_b32_e32 v39, v56
	v_mov_b32_e32 v24, v56
	v_mov_b32_e32 v25, v56
	v_mov_b32_e32 v26, v56
	v_mov_b32_e32 v27, v56
	v_mov_b32_e32 v16, v56
	v_mov_b32_e32 v17, v56
	v_mov_b32_e32 v18, v56
	v_mov_b32_e32 v19, v56
	v_mov_b32_e32 v28, v56
	v_mov_b32_e32 v29, v56
	v_mov_b32_e32 v30, v56
	v_mov_b32_e32 v31, v56
	v_mov_b32_e32 v20, v56
	v_mov_b32_e32 v21, v56
	v_mov_b32_e32 v22, v56
	v_mov_b32_e32 v23, v56
	v_mov_b32_e32 v8, v56
	v_mov_b32_e32 v9, v56
	v_mov_b32_e32 v10, v56
	v_mov_b32_e32 v11, v56
	v_mov_b32_e32 v0, v56
	v_mov_b32_e32 v1, v56
	v_mov_b32_e32 v2, v56
	v_mov_b32_e32 v3, v56
	v_mov_b32_e32 v12, v56
	v_mov_b32_e32 v13, v56
	v_mov_b32_e32 v14, v56
	v_mov_b32_e32 v15, v56
	v_mov_b32_e32 v4, v56
	v_mov_b32_e32 v5, v56
	v_mov_b32_e32 v6, v56
	v_mov_b32_e32 v7, v56
	v_ashrrev_i32_e32 v140, 8, v141
	v_readfirstlane_b32 s99, v151
	v_lshl_add_u32 v174, v140, 14, v129
	v_mov_b32_e32 v161, v131
	v_lshl_add_u64 v[162:163], v[138:139], 0, s[20:21]
	v_lshl_add_u64 v[164:165], v[136:137], 0, s[20:21]
	v_lshl_add_u64 v[166:167], v[138:139], 0, s[22:23]
	v_lshl_add_u64 v[168:169], v[136:137], 0, s[22:23]
	v_mov_b64_e32 v[170:171], v[134:135]
	v_mov_b64_e32 v[172:173], v[132:133]
	v_mov_b32_e32 v160, v174
	s_add_u32 s98, s99, 0x18000
	s_branch .LBB0_1266
.LBB0_1265:
	s_waitcnt lgkmcnt(0)
	s_barrier
	s_setprio 1
	s_waitcnt lgkmcnt(0)
	v_mfma_f32_16x16x32_bf16 v[56:59], v[112:115], v[108:111], v[56:59]
	v_mfma_f32_16x16x32_bf16 v[48:51], v[116:119], v[108:111], v[48:51]
	v_mfma_f32_16x16x32_bf16 v[60:63], v[120:123], v[108:111], v[60:63]
	v_mfma_f32_16x16x32_bf16 v[52:55], v[124:127], v[108:111], v[52:55]
	v_mfma_f32_16x16x32_bf16 v[40:43], v[112:115], v[104:107], v[40:43]
	v_mfma_f32_16x16x32_bf16 v[32:35], v[116:119], v[104:107], v[32:35]
	v_mfma_f32_16x16x32_bf16 v[44:47], v[120:123], v[104:107], v[44:47]
	v_mfma_f32_16x16x32_bf16 v[36:39], v[124:127], v[104:107], v[36:39]
	s_cmp_gt_u32 s58, 13
	s_cbranch_scc1 .Lgc6_skd3
	s_add_u32 m0, s98, 0x6000
	s_nop 0
	global_load_lds_dwordx4 v[168:169], off
; #define STAGE_ALL(bufi, kt) do { STAGEA(SA(bufi, 0), brow, kt); STAGEA(SA(bufi, 1), brow + HALF, kt); STAGEB(SB(bufi), bcol, kt); } while (0)
; #define WAIT_V(n) asm volatile("s_waitcnt vmcnt(" #n ")" ::: "memory")
; #define BAR __builtin_amdgcn_s_barrier()
;     ...
;     for (int t = 0; t < nt; ++t) {
;       const char* pa = (const char*)SA(b, wr >> 1);
;       const char* pb = (const char*)SB(b);
;       bf16x8 At[4][2], Bf[4][2];
; #pragma unroll
;       for (int m = 0; m < 4; ++m)
; #pragma unroll
;         for (int k = 0; k < 2; ++k) At[m][k] = *reinterpret_cast<const bf16x8*>(pa + lds_byte((wr & 1) * 64 + m * 16 + fr, k * 32 + fq * 8));
; #pragma unroll
;       for (int n = 0; n < 4; ++n)
; #pragma unroll
;         for (int k = 0; k < 2; ++k) Bf[n][k] = *reinterpret_cast<const bf16x8*>(pb + lds_byte(wc * 64 + n * 16 + fr, k * 32 + fq * 8));
;       if (t + 2 < nt) { const int b2 = (b == 0) ? 2 : b - 1; STAGE_ALL(b2, t + 2); WAIT_V(6); } else { WAIT_V(0); }
;       asm volatile("s_waitcnt lgkmcnt(0)" ::: "memory");
;       __builtin_amdgcn_sched_barrier(0);
;       BAR;
;       __builtin_amdgcn_sched_barrier(0);
;       __builtin_amdgcn_s_setprio(1);
; #pragma unroll
;       for (int k = 0; k < 2; ++k)
; #pragma unroll
;         for (int m = 0; m < 4; ++m)
; #pragma unroll
;           for (int n = 0; n < 4; ++n) acc[m][n] = __builtin_amdgcn_mfma_f32_16x16x32_bf16(Bf[n][k], At[m][k], acc[m][n], 0, 0, 0);
;       __builtin_amdgcn_s_setprio(0);
;       __builtin_amdgcn_sched_barrier(0);
;       BAR;
;       __builtin_amdgcn_sched_barrier(0);
;       b = (b == 2) ? 0 : b + 1;
;     }
.Lgc6_skd3:
	v_mfma_f32_16x16x32_bf16 v[24:27], v[112:115], v[100:103], v[24:27]
	v_mfma_f32_16x16x32_bf16 v[16:19], v[116:119], v[100:103], v[16:19]
	v_mfma_f32_16x16x32_bf16 v[28:31], v[120:123], v[100:103], v[28:31]
	v_mfma_f32_16x16x32_bf16 v[20:23], v[124:127], v[100:103], v[20:23]
	v_mfma_f32_16x16x32_bf16 v[8:11], v[112:115], v[96:99], v[8:11]
	v_mfma_f32_16x16x32_bf16 v[0:3], v[116:119], v[96:99], v[0:3]
	v_mfma_f32_16x16x32_bf16 v[12:15], v[120:123], v[96:99], v[12:15]
	v_mfma_f32_16x16x32_bf16 v[4:7], v[124:127], v[96:99], v[4:7]
	s_cmp_gt_u32 s58, 13
	s_cbranch_scc1 .Lgc6_skd4
	s_add_u32 m0, s98, 0x8000
	s_nop 0
	global_load_lds_dwordx4 v[170:171], off
.Lgc6_skd4:
	v_mfma_f32_16x16x32_bf16 v[56:59], v[80:83], v[76:79], v[56:59]
	v_mfma_f32_16x16x32_bf16 v[48:51], v[84:87], v[76:79], v[48:51]
	v_mfma_f32_16x16x32_bf16 v[60:63], v[88:91], v[76:79], v[60:63]
	v_mfma_f32_16x16x32_bf16 v[52:55], v[92:95], v[76:79], v[52:55]
	v_mfma_f32_16x16x32_bf16 v[40:43], v[80:83], v[72:75], v[40:43]
	v_mfma_f32_16x16x32_bf16 v[32:35], v[84:87], v[72:75], v[32:35]
	v_mfma_f32_16x16x32_bf16 v[44:47], v[88:91], v[72:75], v[44:47]
	v_mfma_f32_16x16x32_bf16 v[36:39], v[92:95], v[72:75], v[36:39]
	s_cmp_gt_u32 s58, 13
	s_cbranch_scc1 .Lgc6_skd5
	s_add_u32 m0, s98, 0xa000
	s_nop 0
	global_load_lds_dwordx4 v[172:173], off
.Lgc6_skd5:
	v_mfma_f32_16x16x32_bf16 v[24:27], v[80:83], v[68:71], v[24:27]
	v_mfma_f32_16x16x32_bf16 v[16:19], v[84:87], v[68:71], v[16:19]
	v_mfma_f32_16x16x32_bf16 v[28:31], v[88:91], v[68:71], v[28:31]
	v_mfma_f32_16x16x32_bf16 v[20:23], v[92:95], v[68:71], v[20:23]
	v_mfma_f32_16x16x32_bf16 v[8:11], v[80:83], v[64:67], v[8:11]
	v_mfma_f32_16x16x32_bf16 v[0:3], v[84:87], v[64:67], v[0:3]
	v_mfma_f32_16x16x32_bf16 v[12:15], v[88:91], v[64:67], v[12:15]
	v_mfma_f32_16x16x32_bf16 v[4:7], v[92:95], v[64:67], v[4:7]
	s_setprio 0
	s_add_i32 s36, s43, 1
	s_cmp_lg_u32 s43, 2
	s_cselect_b32 s43, s36, 0
	s_add_i32 s58, s58, 1
	s_add_u32 s10, s10, 0x80
	s_addc_u32 s11, s11, 0
	s_mul_i32 s36, s43, 0xc000
	v_add_u32_e32 v160, s36, v174
	v_add_u32_e32 v161, s36, v131
	s_mul_i32 s36, s43, 0x6000
	s_addk_i32 s36, 0xa000
	s_cmp_lg_u32 s43, 0
	s_cselect_b32 s36, s36, 0xc000
	s_lshl_b32 s36, s36, 1
	s_add_u32 s98, s36, s99
	v_lshl_add_u64 v[162:163], v[162:163], 0, s[14:15]
	v_lshl_add_u64 v[164:165], v[164:165], 0, s[14:15]
	v_lshl_add_u64 v[166:167], v[166:167], 0, s[14:15]
	v_lshl_add_u64 v[168:169], v[168:169], 0, s[14:15]
	v_lshl_add_u64 v[170:171], v[170:171], 0, s[14:15]
	v_lshl_add_u64 v[172:173], v[172:173], 0, s[14:15]
	s_barrier
	s_cmpk_eq_i32 s10, 0x800
	s_cbranch_scc1 .LBB0_1270
.LBB0_1266:
	ds_read_b128 v[108:111], v160
	ds_read_b128 v[76:79], v160 offset:1024
	ds_read_b128 v[104:107], v160 offset:2048
	ds_read_b128 v[72:75], v160 offset:3072
	ds_read_b128 v[100:103], v160 offset:4096
	ds_read_b128 v[68:71], v160 offset:5120
	ds_read_b128 v[96:99], v160 offset:6144
	ds_read_b128 v[64:67], v160 offset:7168
	ds_read_b128 v[112:115], v161 offset:32768
	ds_read_b128 v[80:83], v161 offset:33792
	ds_read_b128 v[116:119], v161 offset:34816
	ds_read_b128 v[84:87], v161 offset:35840
	ds_read_b128 v[120:123], v161 offset:36864
	ds_read_b128 v[88:91], v161 offset:37888
	ds_read_b128 v[124:127], v161 offset:38912
	ds_read_b128 v[92:95], v161 offset:39936
	s_cmp_gt_u32 s58, 13
	s_cbranch_scc1 .Lgc6_nostage
	s_mov_b32 m0, s98
	s_nop 0
	global_load_lds_dwordx4 v[162:163], off
	s_add_u32 m0, s98, 0x2000
	s_nop 0
	global_load_lds_dwordx4 v[164:165], off
	s_add_u32 m0, s98, 0x4000
	s_nop 0
	global_load_lds_dwordx4 v[166:167], off
	s_waitcnt vmcnt(3)
	s_branch .LBB0_1265

; #define LAS __attribute__((address_space(3)))
; __global__ void __launch_bounds__(NTHR) fwd_megakernel(Params p_unused) {
;   cg::grid_group grid = cg::this_grid();
;   __shared__ uint4 xb_words;
;   if (threadIdx.x == 0) xb_words = make_uint4(0u, 0u, 0u, 0u);
;   __syncthreads();
;   XcdBarrier xb = xcd_barrier_post((unsigned*)(((CParams*)__builtin_amdgcn_kernarg_segment_ptr())->ws + B_BAR), (volatile LAS unsigned*)&xb_words);
;   grid.sync();
	.amdhsa_kernel _Z14fwd_megakernel6Params
		.amdhsa_group_segment_fixed_size 16
		.amdhsa_private_segment_fixed_size 0
		.amdhsa_kernarg_size 496
		.amdhsa_user_sgpr_count 2
		.amdhsa_user_sgpr_dispatch_ptr 0
		.amdhsa_user_sgpr_queue_ptr 0
		.amdhsa_user_sgpr_kernarg_segment_ptr 1
		.amdhsa_user_sgpr_dispatch_id 0
		.amdhsa_user_sgpr_kernarg_preload_length 0
		.amdhsa_user_sgpr_kernarg_preload_offset 0
		.amdhsa_user_sgpr_private_segment_size 0
		.amdhsa_uses_dynamic_stack 0
		.amdhsa_enable_private_segment 0
		.amdhsa_system_sgpr_workgroup_id_x 1
		.amdhsa_system_sgpr_workgroup_id_y 0
		.amdhsa_system_sgpr_workgroup_id_z 0
		.amdhsa_system_sgpr_workgroup_info 0
		.amdhsa_system_vgpr_workitem_id 2
		.amdhsa_next_free_vgpr 256
		.amdhsa_next_free_sgpr 102
		.amdhsa_accum_offset 256
		.amdhsa_reserve_vcc 1
		.amdhsa_float_round_mode_32 0
		.amdhsa_float_round_mode_16_64 0
		.amdhsa_float_denorm_mode_32 3
		.amdhsa_float_denorm_mode_16_64 3
		.amdhsa_dx10_clamp 1
		.amdhsa_ieee_mode 1
		.amdhsa_fp16_overflow 0
		.amdhsa_tg_split 0
		.amdhsa_exception_fp_ieee_invalid_op 0
		.amdhsa_exception_fp_denorm_src 0
		.amdhsa_exception_fp_ieee_div_zero 0
		.amdhsa_exception_fp_ieee_overflow 0
		.amdhsa_exception_fp_ieee_underflow 0
		.amdhsa_exception_fp_ieee_inexact 0
		.amdhsa_exception_int_div_zero 0
	.end_amdhsa_kernel

; #define LAS __attribute__((address_space(3)))
; __global__ void __launch_bounds__(NTHR) fwd_megakernel(Params p_unused) {
;   cg::grid_group grid = cg::this_grid();
;   __shared__ uint4 xb_words;
;   if (threadIdx.x == 0) xb_words = make_uint4(0u, 0u, 0u, 0u);
;   __syncthreads();
;   XcdBarrier xb = xcd_barrier_post((unsigned*)(((CParams*)__builtin_amdgcn_kernarg_segment_ptr())->ws + B_BAR), (volatile LAS unsigned*)&xb_words);
;   grid.sync();
amdhsa.kernels:
  - .agpr_count:     0
    .args:
      - .offset:         0
        .size:           240
        .value_kind:     by_value
      - .offset:         240
        .size:           4
        .value_kind:     hidden_block_count_x
      - .offset:         244
        .size:           4
        .value_kind:     hidden_block_count_y
      - .offset:         248
        .size:           4
        .value_kind:     hidden_block_count_z
      - .offset:         252
        .size:           2
        .value_kind:     hidden_group_size_x
      - .offset:         254
        .size:           2
        .value_kind:     hidden_group_size_y
      - .offset:         256
        .size:           2
        .value_kind:     hidden_group_size_z
      - .offset:         258
        .size:           2
        .value_kind:     hidden_remainder_x
      - .offset:         260
        .size:           2
        .value_kind:     hidden_remainder_y
      - .offset:         262
        .size:           2
        .value_kind:     hidden_remainder_z
      - .offset:         280
        .size:           8
        .value_kind:     hidden_global_offset_x
      - .offset:         288
        .size:           8
        .value_kind:     hidden_global_offset_y
      - .offset:         296
        .size:           8
        .value_kind:     hidden_global_offset_z
      - .offset:         304
        .size:           2
        .value_kind:     hidden_grid_dims
      - .offset:         328
        .size:           8
        .value_kind:     hidden_multigrid_sync_arg
      - .offset:         360
        .size:           4
        .value_kind:     hidden_dynamic_lds_size
    .group_segment_fixed_size: 16
    .kernarg_segment_align: 8
    .kernarg_segment_size: 496
    .language:       OpenCL C
    .language_version:
      - 2
      - 0
    .max_flat_workgroup_size: 512
    .name:           _Z14fwd_megakernel6Params
    .private_segment_fixed_size: 0
    .sgpr_count:     108
    .sgpr_spill_count: 139
    .symbol:         _Z14fwd_megakernel6Params.kd
    .uniform_work_group_size: 1
    .uses_dynamic_stack: false
    .vgpr_count:     256
    .vgpr_spill_count: 0
    .wavefront_size: 64
